# GEMM epilogues of the out-proj, gate, both residual and FF1 phases store with sc1 (write-through) so the per-phase L2 writeback before each grid barrier has less to flush
# baseline (speedup 1.0000x reference)
; __device__ __forceinline__ unsigned pk_bf16(float lo, float hi) { typedef float f2_t __attribute__((ext_vector_type(2))); typedef __bf16 b2_t __attribute__((ext_vector_type(2))); f2_t v = {lo, hi}; b2_t b = __builtin_convertvector(v, b2_t); return __builtin_bit_cast(unsigned, b); }
;     __device__ __forceinline__ void store8(bf16_t* p, f32x4 v0, f32x4 v1) const {
;         u32x4 w; w.x = pk_bf16(v0[0], v0[1]); w.y = pk_bf16(v0[2], v0[3]); w.z = pk_bf16(v1[0], v1[1]); w.w = pk_bf16(v1[2], v1[3]); *(u32x4*)p = w; }
;     __device__ __forceinline__ void operator()(const f32x4 (&acc)[2][2][4][2], const Unit& u, int wr, int wc, int fr, int fq) const {
;     ...
; #pragma unroll
;                 for (int bj = 0; bj < 2; ++bj) {
;                     const int col8 = u.pn * BM + bj * HALF + wc * 32 + 8 * fq;
;                     f32x4 v0 = acc[ai][bj][m][0] * rs1, v1 = acc[ai][bj][m][1] * rs1;
;                     if (mode == EP_PLAIN) { store8(O + (size_t)row * ldc + col8, v0, v1); }
.LBB0_998:
	v_lshl_add_u32 v144, s49, 8, v140
	v_ashrrev_i32_e32 v145, 31, v144
	v_lshl_or_b32 v146, s48, 8, v142
	v_lshlrev_b64 v[148:149], 11, v[144:145]
	v_ashrrev_i32_e32 v147, 31, v146
	v_lshl_add_u64 v[148:149], s[6:7], 0, v[148:149]
	v_lshlrev_b64 v[146:147], 1, v[146:147]
	v_lshl_add_u64 v[148:149], v[148:149], 0, v[146:147]
	s_mov_b32 s11, 0x40000
	s_mov_b64 s[16:17], 0x40000
	v_cvt_pk_bf16_f32 v62, v62, v63
	v_cvt_pk_bf16_f32 v63, v64, v65
	v_cvt_pk_bf16_f32 v64, v58, v59
	v_add_co_u32_e32 v58, vcc, s11, v148
	v_cvt_pk_bf16_f32 v70, v70, v71
	v_cvt_pk_bf16_f32 v71, v72, v73
	v_cvt_pk_bf16_f32 v72, v66, v67
	v_lshl_add_u64 v[66:67], v[148:149], 0, s[16:17]
	v_addc_co_u32_e32 v59, vcc, 0, v149, vcc
	v_cvt_pk_bf16_f32 v46, v46, v47
	v_cvt_pk_bf16_f32 v47, v48, v49
	v_cvt_pk_bf16_f32 v48, v42, v43
	v_cvt_pk_bf16_f32 v49, v44, v45
	s_mov_b32 s11, 0x48000
	v_cvt_pk_bf16_f32 v110, v110, v111
	v_cvt_pk_bf16_f32 v111, v112, v113
	v_cvt_pk_bf16_f32 v112, v106, v107
	v_or_b32_e32 v106, 16, v144
	global_store_dwordx4 v[66:67], v[46:49], off offset:256 sc1
	s_mov_b64 s[16:17], 0x48000
	v_ashrrev_i32_e32 v107, 31, v106
	v_add_co_u32_e32 v48, vcc, s11, v148
	v_cvt_pk_bf16_f32 v94, v94, v95
	v_cvt_pk_bf16_f32 v95, v96, v97
	v_cvt_pk_bf16_f32 v96, v90, v91
	v_or_b32_e32 v90, 32, v144
	v_lshl_add_u64 v[46:47], v[148:149], 0, s[16:17]
	v_addc_co_u32_e32 v49, vcc, 0, v149, vcc
	v_cvt_pk_bf16_f32 v30, v30, v31
	v_cvt_pk_bf16_f32 v31, v32, v33
	v_cvt_pk_bf16_f32 v32, v26, v27
	v_cvt_pk_bf16_f32 v33, v28, v29
	s_mov_b32 s11, 0x50000
	v_lshlrev_b64 v[106:107], 11, v[106:107]
	v_ashrrev_i32_e32 v91, 31, v90
	v_cvt_pk_bf16_f32 v78, v78, v79
	v_cvt_pk_bf16_f32 v79, v80, v81
	v_cvt_pk_bf16_f32 v80, v74, v75
	v_or_b32_e32 v74, 48, v144
	global_store_dwordx4 v[46:47], v[30:33], off offset:256 sc1
	s_mov_b64 s[16:17], 0x50000
	v_cvt_pk_bf16_f32 v113, v108, v109
	v_add_co_u32_e32 v32, vcc, s11, v148
	v_lshl_add_u64 v[106:107], s[6:7], 0, v[106:107]
	v_lshlrev_b64 v[90:91], 11, v[90:91]
	v_ashrrev_i32_e32 v75, 31, v74
	v_lshl_add_u64 v[30:31], v[148:149], 0, s[16:17]
	v_addc_co_u32_e32 v33, vcc, 0, v149, vcc
	v_cvt_pk_bf16_f32 v14, v14, v15
	v_cvt_pk_bf16_f32 v15, v16, v17
	v_cvt_pk_bf16_f32 v16, v10, v11
	v_cvt_pk_bf16_f32 v17, v12, v13
	s_mov_b32 s11, 0x58000
	global_store_dwordx4 v[148:149], v[110:113], off offset:256 sc1
	v_cvt_pk_bf16_f32 v97, v92, v93
	v_lshl_add_u64 v[90:91], s[6:7], 0, v[90:91]
	v_lshl_add_u64 v[110:111], v[106:107], 0, v[146:147]
	v_lshlrev_b64 v[74:75], 11, v[74:75]
	global_store_dwordx4 v[30:31], v[14:17], off offset:256 sc1
	global_store_dwordx4 v[110:111], v[94:97], off offset:256 sc1
	v_cvt_pk_bf16_f32 v81, v76, v77
	v_add_co_u32_e32 v16, vcc, s11, v148
	v_lshl_add_u64 v[94:95], v[90:91], 0, v[146:147]
	v_lshl_add_u64 v[74:75], s[6:7], 0, v[74:75]
	s_mov_b64 s[16:17], 0x58000
	v_addc_co_u32_e32 v17, vcc, 0, v149, vcc
	v_cvt_pk_bf16_f32 v126, v126, v127
	v_cvt_pk_bf16_f32 v127, v128, v129
	v_cvt_pk_bf16_f32 v128, v122, v123
	v_cvt_pk_bf16_f32 v129, v124, v125
	v_cvt_pk_bf16_f32 v106, v118, v119
	v_cvt_pk_bf16_f32 v107, v120, v121
	v_cvt_pk_bf16_f32 v108, v114, v115
	v_cvt_pk_bf16_f32 v109, v116, v117
	v_cvt_pk_bf16_f32 v90, v102, v103
	v_cvt_pk_bf16_f32 v91, v104, v105
	v_cvt_pk_bf16_f32 v92, v98, v99
	v_cvt_pk_bf16_f32 v93, v100, v101
	global_store_dwordx4 v[94:95], v[78:81], off offset:256 sc1
	v_cvt_pk_bf16_f32 v76, v82, v83
	v_cvt_pk_bf16_f32 v77, v84, v85
	v_lshl_add_u64 v[78:79], v[74:75], 0, v[146:147]
	v_cvt_pk_bf16_f32 v74, v86, v87
	v_cvt_pk_bf16_f32 v75, v88, v89
	v_cvt_pk_bf16_f32 v73, v68, v69
	v_cvt_pk_bf16_f32 v65, v60, v61
	v_cvt_pk_bf16_f32 v42, v54, v55
	v_cvt_pk_bf16_f32 v43, v56, v57
	v_cvt_pk_bf16_f32 v44, v50, v51
	v_cvt_pk_bf16_f32 v45, v52, v53
	v_cvt_pk_bf16_f32 v26, v38, v39
	v_cvt_pk_bf16_f32 v27, v40, v41
	v_cvt_pk_bf16_f32 v28, v34, v35
	v_cvt_pk_bf16_f32 v29, v36, v37
	v_lshl_add_u64 v[14:15], v[148:149], 0, s[16:17]
	v_cvt_pk_bf16_f32 v10, v22, v23
	v_cvt_pk_bf16_f32 v11, v24, v25
	v_cvt_pk_bf16_f32 v12, v18, v19
	v_cvt_pk_bf16_f32 v13, v20, v21
	v_cvt_pk_bf16_f32 v6, v6, v7
	v_cvt_pk_bf16_f32 v7, v8, v9
	v_cvt_pk_bf16_f32 v8, v2, v3
	v_cvt_pk_bf16_f32 v9, v4, v5
	s_andn2_b64 vcc, exec, s[0:1]
	s_mov_b64 s[0:1], -1
	global_store_dwordx4 v[148:149], v[126:129], off sc1
	global_store_dwordx4 v[110:111], v[106:109], off sc1
	global_store_dwordx4 v[94:95], v[90:93], off sc1
	global_store_dwordx4 v[78:79], v[74:77], off sc1
	global_store_dwordx4 v[78:79], v[70:73], off offset:256 sc1
	global_store_dwordx4 v[58:59], v[62:65], off sc1
	global_store_dwordx4 v[48:49], v[42:45], off sc1
	global_store_dwordx4 v[32:33], v[26:29], off sc1
	global_store_dwordx4 v[16:17], v[10:13], off sc1
	global_store_dwordx4 v[14:15], v[6:9], off offset:256 sc1
	s_cbranch_vccnz .LBB0_991
	s_andn2_b64 vcc, exec, s[4:5]
	s_cbranch_vccnz .LBB0_990
	s_barrier
	s_branch .LBB0_990

; __device__ __forceinline__ float sigmoidf_(float x) { return __builtin_amdgcn_rcpf(1.0f + __builtin_amdgcn_exp2f(-1.4426950408889634f * x)); }
;     __device__ __forceinline__ void operator()(const f32x4 (&acc)[2][2][4][2], const Unit& u, int wr, int wc, int fr, int fq) const {
;     ...
;         if (rs_n > 0) {
;             f32x4 part[2][4];
; #pragma unroll
;             for (int ai = 0; ai < 2; ++ai)
; #pragma unroll
;                 for (int m = 0; m < 4; ++m) {
;                     part[ai][m] = (f32x4){0.f, 0.f, 0.f, 0.f};
;                     if (4 * fq < rs_n) part[ai][m] = *(const f32x4*)(rs + (size_t)(row0 + ai * HALF + m * 16) * rs_ld + rs_off + 4 * fq);
;                 }
; #pragma unroll
;             for (int ai = 0; ai < 2; ++ai)
; #pragma unroll
;                 for (int m = 0; m < 4; ++m) {
;                     float t = (part[ai][m][0] + part[ai][m][1]) + (part[ai][m][2] + part[ai][m][3]);
;                     t += __shfl_xor(t, 16); t += __shfl_xor(t, 32);
;                     rsc[ai][m] = __builtin_amdgcn_rsqf(t * rs_inv + EPS);
;                 }
;     ...
;                 if (mode == EP_GATE) {
;                     const size_t off = (size_t)row * DM + u.pn * 128 + wc * 32 + 8 * fq;
;                     const f32x4 a0 = acc[ai][0][m][0] * rs1, a1 = acc[ai][0][m][1] * rs1, b0 = acc[ai][1][m][0] * rs1, b1 = acc[ai][1][m][1] * rs1;
;                     const u32x4 y1 = yall[ai][m][0], y2 = yall[ai][m][1];
;                     f32x4 r0, r1;
;                     r0[0] = sigmoidf_(a0[0]) * bf_lo(y1.x) + sigmoidf_(b0[0]) * bf_lo(y2.x); r0[1] = sigmoidf_(a0[1]) * bf_hi(y1.x) + sigmoidf_(b0[1]) * bf_hi(y2.x);
.LBB0_1082:
	v_lshl_add_u32 v210, s22, 8, v171
	v_ashrrev_i32_e32 v211, 31, v210
	v_lshlrev_b64 v[130:131], 6, v[210:211]
	v_lshl_add_u64 v[130:131], v[172:173], 0, v[130:131]
	global_load_dwordx4 v[130:133], v[130:131], off
	v_or_b32_e32 v206, 16, v210
	v_ashrrev_i32_e32 v207, 31, v206
	v_lshlrev_b64 v[134:135], 6, v[206:207]
	v_lshl_add_u64 v[134:135], v[172:173], 0, v[134:135]
	global_load_dwordx4 v[134:137], v[134:135], off
	v_or_b32_e32 v204, 32, v210
	v_ashrrev_i32_e32 v205, 31, v204
	v_lshlrev_b64 v[138:139], 6, v[204:205]
	v_lshl_add_u64 v[138:139], v[172:173], 0, v[138:139]
	global_load_dwordx4 v[138:141], v[138:139], off
	v_or_b32_e32 v198, 48, v210
	v_ashrrev_i32_e32 v199, 31, v198
	v_lshlrev_b64 v[142:143], 6, v[198:199]
	v_lshl_add_u64 v[142:143], v[172:173], 0, v[142:143]
	global_load_dwordx4 v[142:145], v[142:143], off
	v_add_u32_e32 v188, 0x80, v210
	v_ashrrev_i32_e32 v189, 31, v188
	v_lshlrev_b64 v[146:147], 6, v[188:189]
	v_lshl_add_u64 v[146:147], v[172:173], 0, v[146:147]
	global_load_dwordx4 v[146:149], v[146:147], off
	v_add_u32_e32 v184, 0x90, v210
	v_ashrrev_i32_e32 v185, 31, v184
	v_lshlrev_b64 v[150:151], 6, v[184:185]
	v_lshl_add_u64 v[150:151], v[172:173], 0, v[150:151]
	global_load_dwordx4 v[150:153], v[150:151], off
	v_add_u32_e32 v182, 0xa0, v210
	v_ashrrev_i32_e32 v183, 31, v182
	v_lshlrev_b64 v[154:155], 6, v[182:183]
	v_lshl_add_u64 v[154:155], v[172:173], 0, v[154:155]
	global_load_dwordx4 v[154:157], v[154:155], off
	v_add_u32_e32 v178, 0xb0, v210
	v_ashrrev_i32_e32 v179, 31, v178
	v_lshlrev_b64 v[158:159], 6, v[178:179]
	v_lshl_add_u64 v[158:159], v[172:173], 0, v[158:159]
	global_load_dwordx4 v[158:161], v[158:159], off
	s_lshl_b32 s4, s21, 7
	s_ashr_i32 s5, s4, 31
	v_mov_b32_e32 v201, s5
	v_or_b32_e32 v200, s4, v170
	s_lshl_b64 s[4:5], s[4:5], 1
	s_andn2_b64 vcc, exec, s[36:37]
	s_waitcnt vmcnt(0)
	v_mov_b32_e32 v190, v131
	v_mov_b32_e32 v191, v132
	v_mov_b32_e32 v131, v133
	v_pk_add_f32 v[130:131], v[190:191], v[130:131]
	v_mov_b32_e32 v132, v195
	v_add_f32_e32 v130, v130, v131
	ds_bpermute_b32 v131, v216, v130
	s_waitcnt lgkmcnt(0)
	v_add_f32_e32 v130, v130, v131
	ds_bpermute_b32 v131, v217, v130
	s_waitcnt lgkmcnt(0)
	v_add_f32_e32 v130, v130, v131
	v_fmamk_f32 v130, v130, 0x3a800000, v195
	v_rsq_f32_e32 v214, v130
	v_mov_b32_e32 v130, v135
	v_mov_b32_e32 v131, v136
	v_mov_b32_e32 v135, v137
	v_pk_add_f32 v[130:131], v[130:131], v[134:135]
	v_pk_mul_f32 v[118:119], v[118:119], v[214:215] op_sel_hi:[1,0]
	v_add_f32_e32 v130, v130, v131
	ds_bpermute_b32 v131, v216, v130
	v_pk_mul_f32 v[126:127], v[126:127], v[214:215] op_sel_hi:[1,0]
	v_mul_f32_e32 v118, 0xbfb8aa3b, v118
	v_mul_f32_e32 v119, 0xbfb8aa3b, v119
	v_mul_f32_e32 v126, 0xbfb8aa3b, v126
	s_waitcnt lgkmcnt(0)
	v_add_f32_e32 v130, v130, v131
	ds_bpermute_b32 v131, v217, v130
	v_exp_f32_e32 v118, v118
	v_mul_f32_e32 v127, 0xbfb8aa3b, v127
	v_exp_f32_e32 v119, v119
	v_exp_f32_e32 v126, v126
	s_waitcnt lgkmcnt(0)
	v_add_f32_e32 v130, v130, v131
	v_fmamk_f32 v130, v130, 0x3a800000, v132
	v_rsq_f32_e32 v212, v130
	v_mov_b32_e32 v130, v139
	v_mov_b32_e32 v131, v140
	v_mov_b32_e32 v139, v141
	v_pk_add_f32 v[130:131], v[130:131], v[138:139]
	v_exp_f32_e32 v127, v127
	v_add_f32_e32 v130, v130, v131
	ds_bpermute_b32 v131, v216, v130
	v_add_f32_e32 v118, 1.0, v118
	v_add_f32_e32 v119, 1.0, v119
	v_add_f32_e32 v126, 1.0, v126
	v_rcp_f32_e32 v118, v118
	s_waitcnt lgkmcnt(0)
	v_add_f32_e32 v130, v130, v131
	ds_bpermute_b32 v131, v217, v130
	v_add_f32_e32 v127, 1.0, v127
	v_rcp_f32_e32 v119, v119
	v_rcp_f32_e32 v126, v126
	v_rcp_f32_e32 v127, v127
	s_waitcnt lgkmcnt(0)
	v_add_f32_e32 v130, v130, v131
	v_fmamk_f32 v130, v130, 0x3a800000, v132
	v_rsq_f32_e32 v208, v130
	v_mov_b32_e32 v130, v143
	v_mov_b32_e32 v131, v144
	v_mov_b32_e32 v143, v145
	v_pk_add_f32 v[130:131], v[130:131], v[142:143]
	v_pk_mul_f32 v[120:121], v[120:121], v[214:215] op_sel_hi:[1,0]
	v_add_f32_e32 v130, v130, v131
	ds_bpermute_b32 v131, v216, v130
	v_pk_mul_f32 v[128:129], v[128:129], v[214:215] op_sel_hi:[1,0]
	v_mul_f32_e32 v120, 0xbfb8aa3b, v120
	v_mul_f32_e32 v121, 0xbfb8aa3b, v121
	v_pk_mul_f32 v[114:115], v[114:115], v[214:215] op_sel_hi:[1,0]
	s_waitcnt lgkmcnt(0)
	v_add_f32_e32 v130, v130, v131
	ds_bpermute_b32 v131, v217, v130
	v_exp_f32_e32 v120, v120
	v_exp_f32_e32 v121, v121
	v_pk_mul_f32 v[122:123], v[122:123], v[214:215] op_sel_hi:[1,0]
	v_mul_f32_e32 v114, 0xbfb8aa3b, v114
	s_waitcnt lgkmcnt(0)
	v_add_f32_e32 v130, v130, v131
	v_fmamk_f32 v130, v130, 0x3a800000, v132
	v_rsq_f32_e32 v202, v130
	v_mov_b32_e32 v130, v147
	v_mov_b32_e32 v131, v148
	v_mov_b32_e32 v147, v149
	v_pk_add_f32 v[130:131], v[130:131], v[146:147]
	v_mul_f32_e32 v115, 0xbfb8aa3b, v115
	v_add_f32_e32 v130, v130, v131
	ds_bpermute_b32 v131, v216, v130
	v_mul_f32_e32 v122, 0xbfb8aa3b, v122
	v_exp_f32_e32 v114, v114
	v_mul_f32_e32 v123, 0xbfb8aa3b, v123
	v_exp_f32_e32 v115, v115
	s_waitcnt lgkmcnt(0)
	v_add_f32_e32 v130, v130, v131
	ds_bpermute_b32 v131, v217, v130
	v_exp_f32_e32 v122, v122
	v_exp_f32_e32 v123, v123
	v_add_f32_e32 v120, 1.0, v120
	v_add_f32_e32 v121, 1.0, v121
	s_waitcnt lgkmcnt(0)
	v_add_f32_e32 v130, v130, v131
	v_fmamk_f32 v130, v130, 0x3a800000, v132
	v_rsq_f32_e32 v196, v130
	v_mov_b32_e32 v130, v151
	v_mov_b32_e32 v131, v152
	v_mov_b32_e32 v151, v153
	v_pk_add_f32 v[130:131], v[130:131], v[150:151]
	v_rcp_f32_e32 v120, v120
	v_add_f32_e32 v130, v130, v131
	ds_bpermute_b32 v131, v216, v130
	v_rcp_f32_e32 v121, v121
	v_add_f32_e32 v114, 1.0, v114
	v_add_f32_e32 v115, 1.0, v115
	v_add_f32_e32 v122, 1.0, v122
	s_waitcnt lgkmcnt(0)
;     __device__ __forceinline__ void operator()(const f32x4 (&acc)[2][2][4][2], const Unit& u, int wr, int wc, int fr, int fq) const {
;     ...
; #pragma unroll
;             for (int ai = 0; ai < 2; ++ai)
; #pragma unroll
;                 for (int m = 0; m < 4; ++m) {
;                     float t = (part[ai][m][0] + part[ai][m][1]) + (part[ai][m][2] + part[ai][m][3]);
;                     t += __shfl_xor(t, 16); t += __shfl_xor(t, 32);
;                     rsc[ai][m] = __builtin_amdgcn_rsqf(t * rs_inv + EPS);
;                 }
;     ...
;                 if (mode == EP_GATE) {
; #pragma unroll
;                     for (int m = 0; m < 4; ++m) { const size_t off = (size_t)(row0 + ai * HALF + m * 16) * DM + u.pn * 128 + wc * 32 + 8 * fq; yall[ai][m][0] = *(const u32x4*)(Y1 + off); yall[ai][m][1] = *(const u32x4*)(Y2 + off); }
	v_add_f32_e32 v130, v130, v131
	ds_bpermute_b32 v131, v217, v130
	v_rcp_f32_e32 v114, v114
	v_add_f32_e32 v123, 1.0, v123
	v_rcp_f32_e32 v115, v115
	v_rcp_f32_e32 v122, v122
	s_waitcnt lgkmcnt(0)
	v_add_f32_e32 v130, v130, v131
	v_fmamk_f32 v130, v130, 0x3a800000, v132
	v_rsq_f32_e32 v190, v130
	v_mov_b32_e32 v130, v155
	v_mov_b32_e32 v131, v156
	v_mov_b32_e32 v155, v157
	v_pk_add_f32 v[130:131], v[130:131], v[154:155]
	v_rcp_f32_e32 v123, v123
	v_add_f32_e32 v130, v130, v131
	ds_bpermute_b32 v131, v216, v130
	v_pk_mul_f32 v[116:117], v[116:117], v[214:215] op_sel_hi:[1,0]
	v_pk_mul_f32 v[124:125], v[124:125], v[214:215] op_sel_hi:[1,0]
	v_mul_f32_e32 v117, 0xbfb8aa3b, v117
	v_exp_f32_e32 v117, v117
	s_waitcnt lgkmcnt(0)
	v_add_f32_e32 v130, v130, v131
	ds_bpermute_b32 v131, v217, v130
	v_pk_mul_f32 v[102:103], v[102:103], v[212:213] op_sel_hi:[1,0]
	v_add_f32_e32 v117, 1.0, v117
	v_rcp_f32_e32 v117, v117
	v_pk_mul_f32 v[110:111], v[110:111], v[212:213] op_sel_hi:[1,0]
	s_waitcnt lgkmcnt(0)
	v_add_f32_e32 v130, v130, v131
	v_fmamk_f32 v130, v130, 0x3a800000, v132
	v_rsq_f32_e32 v186, v130
	v_mov_b32_e32 v130, v159
	v_mov_b32_e32 v131, v160
	v_mov_b32_e32 v159, v161
	v_pk_add_f32 v[130:131], v[130:131], v[158:159]
	v_mul_f32_e32 v102, 0xbfb8aa3b, v102
	v_add_f32_e32 v130, v130, v131
	ds_bpermute_b32 v131, v216, v130
	v_mul_f32_e32 v103, 0xbfb8aa3b, v103
	v_mul_f32_e32 v110, 0xbfb8aa3b, v110
	v_exp_f32_e32 v102, v102
	v_mul_f32_e32 v111, 0xbfb8aa3b, v111
	s_waitcnt lgkmcnt(0)
	v_add_f32_e32 v130, v130, v131
	ds_bpermute_b32 v131, v217, v130
	v_exp_f32_e32 v103, v103
	v_exp_f32_e32 v110, v110
	v_exp_f32_e32 v111, v111
	v_add_f32_e32 v102, 1.0, v102
	s_waitcnt lgkmcnt(0)
	v_add_f32_e32 v130, v130, v131
	v_fmamk_f32 v130, v130, 0x3a800000, v132
	v_rsq_f32_e32 v180, v130
	v_lshlrev_b64 v[130:131], 10, v[210:211]
	v_lshl_add_u64 v[130:131], v[130:131], 0, v[200:201]
	v_lshlrev_b64 v[130:131], 1, v[130:131]
	v_lshl_add_u64 v[132:133], s[38:39], 0, v[130:131]
	v_lshl_add_u64 v[130:131], s[42:43], 0, v[130:131]
	global_load_dwordx4 v[154:157], v[132:133], off
	global_load_dwordx4 v[158:161], v[130:131], off
	v_lshlrev_b64 v[130:131], 10, v[206:207]
	v_lshl_add_u64 v[130:131], v[130:131], 0, v[200:201]
	v_lshlrev_b64 v[130:131], 1, v[130:131]
	v_lshl_add_u64 v[132:133], s[38:39], 0, v[130:131]
	v_lshl_add_u64 v[130:131], s[42:43], 0, v[130:131]
	global_load_dwordx4 v[146:149], v[132:133], off
	global_load_dwordx4 v[150:153], v[130:131], off
	v_lshlrev_b64 v[130:131], 10, v[204:205]
	v_lshl_add_u64 v[130:131], v[130:131], 0, v[200:201]
	v_lshlrev_b64 v[130:131], 1, v[130:131]
	v_lshl_add_u64 v[132:133], s[38:39], 0, v[130:131]
	v_lshl_add_u64 v[130:131], s[42:43], 0, v[130:131]
	global_load_dwordx4 v[138:141], v[132:133], off
	global_load_dwordx4 v[142:145], v[130:131], off
	v_lshlrev_b64 v[130:131], 10, v[198:199]
	v_lshl_add_u64 v[130:131], v[130:131], 0, v[200:201]
	v_lshlrev_b64 v[134:135], 1, v[130:131]
	v_lshl_add_u64 v[130:131], s[38:39], 0, v[134:135]
	v_lshl_add_u64 v[134:135], s[42:43], 0, v[134:135]
	global_load_dwordx4 v[130:133], v[130:131], off
	v_add_f32_e32 v103, 1.0, v103
	global_load_dwordx4 v[134:137], v[134:135], off
	v_add_f32_e32 v110, 1.0, v110
	v_rcp_f32_e32 v102, v102
	v_add_f32_e32 v111, 1.0, v111
	v_rcp_f32_e32 v103, v103
	v_rcp_f32_e32 v110, v110
	v_rcp_f32_e32 v111, v111
	v_pk_mul_f32 v[104:105], v[104:105], v[212:213] op_sel_hi:[1,0]
	v_pk_mul_f32 v[112:113], v[112:113], v[212:213] op_sel_hi:[1,0]
	v_mul_f32_e32 v104, 0xbfb8aa3b, v104
	v_mul_f32_e32 v105, 0xbfb8aa3b, v105
	v_pk_mul_f32 v[98:99], v[98:99], v[212:213] op_sel_hi:[1,0]
	v_exp_f32_e32 v104, v104
	v_exp_f32_e32 v105, v105
	v_pk_mul_f32 v[106:107], v[106:107], v[212:213] op_sel_hi:[1,0]
	v_mul_f32_e32 v98, 0xbfb8aa3b, v98
	v_mul_f32_e32 v99, 0xbfb8aa3b, v99
	v_mul_f32_e32 v106, 0xbfb8aa3b, v106
	v_exp_f32_e32 v98, v98
	v_mul_f32_e32 v107, 0xbfb8aa3b, v107
	v_exp_f32_e32 v99, v99
	v_exp_f32_e32 v106, v106
	v_exp_f32_e32 v107, v107
	v_add_f32_e32 v104, 1.0, v104
	v_add_f32_e32 v105, 1.0, v105
	v_rcp_f32_e32 v104, v104
	v_rcp_f32_e32 v105, v105
	v_add_f32_e32 v98, 1.0, v98
	v_add_f32_e32 v99, 1.0, v99
	v_add_f32_e32 v106, 1.0, v106
	v_rcp_f32_e32 v98, v98
	v_add_f32_e32 v107, 1.0, v107
	v_rcp_f32_e32 v99, v99
	v_rcp_f32_e32 v106, v106
	v_rcp_f32_e32 v107, v107
	v_pk_mul_f32 v[100:101], v[100:101], v[212:213] op_sel_hi:[1,0]
	v_pk_mul_f32 v[108:109], v[108:109], v[212:213] op_sel_hi:[1,0]
	v_mul_f32_e32 v101, 0xbfb8aa3b, v101
	v_exp_f32_e32 v101, v101
	v_pk_mul_f32 v[86:87], v[86:87], v[208:209] op_sel_hi:[1,0]
	v_pk_mul_f32 v[94:95], v[94:95], v[208:209] op_sel_hi:[1,0]
	v_mul_f32_e32 v86, 0xbfb8aa3b, v86
	v_add_f32_e32 v101, 1.0, v101
	v_rcp_f32_e32 v101, v101
	v_mul_f32_e32 v87, 0xbfb8aa3b, v87
	v_mul_f32_e32 v94, 0xbfb8aa3b, v94
	v_exp_f32_e32 v86, v86
	v_mul_f32_e32 v95, 0xbfb8aa3b, v95
	v_exp_f32_e32 v87, v87
	v_exp_f32_e32 v94, v94
	v_exp_f32_e32 v95, v95
	v_add_f32_e32 v86, 1.0, v86
	v_add_f32_e32 v87, 1.0, v87
	v_add_f32_e32 v94, 1.0, v94
	v_rcp_f32_e32 v86, v86
	v_add_f32_e32 v95, 1.0, v95
	v_rcp_f32_e32 v87, v87
	s_waitcnt vmcnt(7)
	v_lshlrev_b32_e32 v192, 16, v154
	s_waitcnt vmcnt(6)
; __device__ __forceinline__ float sigmoidf_(float x) { return __builtin_amdgcn_rcpf(1.0f + __builtin_amdgcn_exp2f(-1.4426950408889634f * x)); }
;     __device__ __forceinline__ void operator()(const f32x4 (&acc)[2][2][4][2], const Unit& u, int wr, int wc, int fr, int fq) const {
;     ...
;                 if (mode == EP_GATE) {
;                     const size_t off = (size_t)row * DM + u.pn * 128 + wc * 32 + 8 * fq;
;                     const f32x4 a0 = acc[ai][0][m][0] * rs1, a1 = acc[ai][0][m][1] * rs1, b0 = acc[ai][1][m][0] * rs1, b1 = acc[ai][1][m][1] * rs1;
;                     const u32x4 y1 = yall[ai][m][0], y2 = yall[ai][m][1];
;                     f32x4 r0, r1;
;                     r0[0] = sigmoidf_(a0[0]) * bf_lo(y1.x) + sigmoidf_(b0[0]) * bf_lo(y2.x); r0[1] = sigmoidf_(a0[1]) * bf_hi(y1.x) + sigmoidf_(b0[1]) * bf_hi(y2.x);
;                     r0[2] = sigmoidf_(a0[2]) * bf_lo(y1.y) + sigmoidf_(b0[2]) * bf_lo(y2.y); r0[3] = sigmoidf_(a0[3]) * bf_hi(y1.y) + sigmoidf_(b0[3]) * bf_hi(y2.y);
;                     r1[0] = sigmoidf_(a1[0]) * bf_lo(y1.z) + sigmoidf_(b1[0]) * bf_lo(y2.z); r1[1] = sigmoidf_(a1[1]) * bf_hi(y1.z) + sigmoidf_(b1[1]) * bf_hi(y2.z);
;                     r1[2] = sigmoidf_(a1[2]) * bf_lo(y1.w) + sigmoidf_(b1[2]) * bf_lo(y2.w); r1[3] = sigmoidf_(a1[3]) * bf_hi(y1.w) + sigmoidf_(b1[3]) * bf_hi(y2.w);
;                     store8(O + off, r0, r1);
	v_lshlrev_b32_e32 v222, 16, v158
	v_and_b32_e32 v223, 0xffff0000, v158
	v_and_b32_e32 v193, 0xffff0000, v154
	v_pk_mul_f32 v[118:119], v[118:119], v[222:223]
	v_lshlrev_b32_e32 v154, 16, v159
	v_pk_fma_f32 v[118:119], v[126:127], v[192:193], v[118:119]
	v_mul_f32_e32 v126, 0xbfb8aa3b, v128
	v_mul_f32_e32 v127, 0xbfb8aa3b, v129
	v_exp_f32_e32 v126, v126
	v_exp_f32_e32 v127, v127
	v_lshlrev_b32_e32 v128, 16, v155
	v_and_b32_e32 v129, 0xffff0000, v155
	v_add_f32_e32 v126, 1.0, v126
	v_add_f32_e32 v127, 1.0, v127
	v_rcp_f32_e32 v126, v126
	v_rcp_f32_e32 v127, v127
	v_and_b32_e32 v155, 0xffff0000, v159
	v_pk_mul_f32 v[120:121], v[120:121], v[154:155]
	v_rcp_f32_e32 v94, v94
	v_pk_fma_f32 v[120:121], v[126:127], v[128:129], v[120:121]
	v_lshlrev_b32_e32 v128, 16, v160
	v_and_b32_e32 v129, 0xffff0000, v160
	v_lshlrev_b32_e32 v126, 16, v156
	v_and_b32_e32 v127, 0xffff0000, v156
	v_pk_mul_f32 v[114:115], v[114:115], v[128:129]
	v_rcp_f32_e32 v95, v95
	v_pk_fma_f32 v[122:123], v[122:123], v[126:127], v[114:115]
	v_mul_f32_e32 v115, 0xbfb8aa3b, v116
	v_exp_f32_e32 v115, v115
	v_mul_f32_e32 v114, 0xbfb8aa3b, v124
	v_exp_f32_e32 v114, v114
	v_lshlrev_b32_e32 v126, 16, v161
	v_add_f32_e32 v115, 1.0, v115
	v_rcp_f32_e32 v116, v115
	v_mul_f32_e32 v115, 0xbfb8aa3b, v125
	v_exp_f32_e32 v115, v115
	v_add_f32_e32 v114, 1.0, v114
	v_rcp_f32_e32 v114, v114
	v_and_b32_e32 v127, 0xffff0000, v161
	v_add_f32_e32 v115, 1.0, v115
	v_rcp_f32_e32 v115, v115
	v_lshlrev_b32_e32 v124, 16, v157
	v_and_b32_e32 v125, 0xffff0000, v157
	v_pk_mul_f32 v[116:117], v[116:117], v[126:127]
	v_pk_mul_f32 v[88:89], v[88:89], v[208:209] op_sel_hi:[1,0]
	v_pk_fma_f32 v[124:125], v[114:115], v[124:125], v[116:117]
	v_lshlrev_b64 v[114:115], 11, v[210:211]
	v_lshl_add_u64 v[114:115], s[40:41], 0, v[114:115]
	v_lshl_add_u64 v[114:115], v[114:115], 0, s[4:5]
	v_lshl_add_u64 v[114:115], v[114:115], 0, s[12:13]
	v_lshl_add_u64 v[126:127], v[114:115], 0, v[0:1]
	v_cvt_pk_bf16_f32 v114, v118, v119
	v_cvt_pk_bf16_f32 v115, v120, v121
	v_cvt_pk_bf16_f32 v116, v122, v123
	v_cvt_pk_bf16_f32 v117, v124, v125
	global_store_dwordx4 v[126:127], v[114:117], off sc1
	v_pk_mul_f32 v[96:97], v[96:97], v[208:209] op_sel_hi:[1,0]
	v_mul_f32_e32 v88, 0xbfb8aa3b, v88
	s_waitcnt vmcnt(5)
	v_lshlrev_b32_e32 v116, 16, v150
	v_and_b32_e32 v117, 0xffff0000, v150
	v_lshlrev_b32_e32 v114, 16, v146
	v_and_b32_e32 v115, 0xffff0000, v146
	v_pk_mul_f32 v[102:103], v[102:103], v[116:117]
	v_mul_f32_e32 v89, 0xbfb8aa3b, v89
	v_pk_fma_f32 v[102:103], v[110:111], v[114:115], v[102:103]
	v_mul_f32_e32 v110, 0xbfb8aa3b, v112
	v_mul_f32_e32 v111, 0xbfb8aa3b, v113
	v_exp_f32_e32 v110, v110
	v_exp_f32_e32 v111, v111
	v_lshlrev_b32_e32 v114, 16, v151
	v_and_b32_e32 v115, 0xffff0000, v151
	v_add_f32_e32 v110, 1.0, v110
	v_add_f32_e32 v111, 1.0, v111
	v_rcp_f32_e32 v110, v110
	v_rcp_f32_e32 v111, v111
	v_lshlrev_b32_e32 v112, 16, v147
	v_and_b32_e32 v113, 0xffff0000, v147
	v_pk_mul_f32 v[104:105], v[104:105], v[114:115]
	v_pk_mul_f32 v[82:83], v[82:83], v[208:209] op_sel_hi:[1,0]
	v_pk_fma_f32 v[104:105], v[110:111], v[112:113], v[104:105]
	v_lshlrev_b32_e32 v112, 16, v152
	v_and_b32_e32 v113, 0xffff0000, v152
	v_lshlrev_b32_e32 v110, 16, v148
	v_and_b32_e32 v111, 0xffff0000, v148
	v_pk_mul_f32 v[98:99], v[98:99], v[112:113]
	v_exp_f32_e32 v88, v88
	v_pk_fma_f32 v[106:107], v[106:107], v[110:111], v[98:99]
	v_mul_f32_e32 v99, 0xbfb8aa3b, v100
	v_exp_f32_e32 v99, v99
	v_mul_f32_e32 v98, 0xbfb8aa3b, v108
	v_exp_f32_e32 v98, v98
	v_lshlrev_b32_e32 v110, 16, v153
	v_add_f32_e32 v99, 1.0, v99
	v_rcp_f32_e32 v100, v99
	v_mul_f32_e32 v99, 0xbfb8aa3b, v109
	v_exp_f32_e32 v99, v99
	v_add_f32_e32 v98, 1.0, v98
	v_rcp_f32_e32 v98, v98
	v_and_b32_e32 v111, 0xffff0000, v153
	v_add_f32_e32 v99, 1.0, v99
	v_rcp_f32_e32 v99, v99
	v_lshlrev_b32_e32 v108, 16, v149
	v_and_b32_e32 v109, 0xffff0000, v149
	v_pk_mul_f32 v[100:101], v[100:101], v[110:111]
	v_exp_f32_e32 v89, v89
	v_pk_fma_f32 v[108:109], v[98:99], v[108:109], v[100:101]
	v_lshlrev_b64 v[98:99], 11, v[206:207]
	v_lshl_add_u64 v[98:99], s[40:41], 0, v[98:99]
	v_lshl_add_u64 v[98:99], v[98:99], 0, s[4:5]
	v_lshl_add_u64 v[98:99], v[98:99], 0, s[12:13]
	v_lshl_add_u64 v[110:111], v[98:99], 0, v[0:1]
	v_cvt_pk_bf16_f32 v98, v102, v103
	v_cvt_pk_bf16_f32 v99, v104, v105
	v_cvt_pk_bf16_f32 v100, v106, v107
	v_cvt_pk_bf16_f32 v101, v108, v109
	s_waitcnt vmcnt(3)
; __device__ __forceinline__ float sigmoidf_(float x) { return __builtin_amdgcn_rcpf(1.0f + __builtin_amdgcn_exp2f(-1.4426950408889634f * x)); }
;     __device__ __forceinline__ void operator()(const f32x4 (&acc)[2][2][4][2], const Unit& u, int wr, int wc, int fr, int fq) const {
;     ...
;                 if (mode == EP_GATE) {
;                     const size_t off = (size_t)row * DM + u.pn * 128 + wc * 32 + 8 * fq;
;                     const f32x4 a0 = acc[ai][0][m][0] * rs1, a1 = acc[ai][0][m][1] * rs1, b0 = acc[ai][1][m][0] * rs1, b1 = acc[ai][1][m][1] * rs1;
;                     const u32x4 y1 = yall[ai][m][0], y2 = yall[ai][m][1];
;                     f32x4 r0, r1;
;                     r0[0] = sigmoidf_(a0[0]) * bf_lo(y1.x) + sigmoidf_(b0[0]) * bf_lo(y2.x); r0[1] = sigmoidf_(a0[1]) * bf_hi(y1.x) + sigmoidf_(b0[1]) * bf_hi(y2.x);
;                     r0[2] = sigmoidf_(a0[2]) * bf_lo(y1.y) + sigmoidf_(b0[2]) * bf_lo(y2.y); r0[3] = sigmoidf_(a0[3]) * bf_hi(y1.y) + sigmoidf_(b0[3]) * bf_hi(y2.y);
;                     r1[0] = sigmoidf_(a1[0]) * bf_lo(y1.z) + sigmoidf_(b1[0]) * bf_lo(y2.z); r1[1] = sigmoidf_(a1[1]) * bf_hi(y1.z) + sigmoidf_(b1[1]) * bf_hi(y2.z);
;                     r1[2] = sigmoidf_(a1[2]) * bf_lo(y1.w) + sigmoidf_(b1[2]) * bf_lo(y2.w); r1[3] = sigmoidf_(a1[3]) * bf_hi(y1.w) + sigmoidf_(b1[3]) * bf_hi(y2.w);
;                     store8(O + off, r0, r1);
	v_lshlrev_b32_e32 v102, 16, v142
	v_and_b32_e32 v103, 0xffff0000, v142
	global_store_dwordx4 v[110:111], v[98:101], off sc1
	v_pk_mul_f32 v[86:87], v[86:87], v[102:103]
	v_pk_mul_f32 v[90:91], v[90:91], v[208:209] op_sel_hi:[1,0]
	v_lshlrev_b32_e32 v100, 16, v138
	v_and_b32_e32 v101, 0xffff0000, v138
	v_pk_fma_f32 v[86:87], v[94:95], v[100:101], v[86:87]
	v_mul_f32_e32 v94, 0xbfb8aa3b, v96
	v_mul_f32_e32 v95, 0xbfb8aa3b, v97
	v_exp_f32_e32 v94, v94
	v_exp_f32_e32 v95, v95
	v_mul_f32_e32 v82, 0xbfb8aa3b, v82
	v_mul_f32_e32 v83, 0xbfb8aa3b, v83
	v_mul_f32_e32 v90, 0xbfb8aa3b, v90
	v_exp_f32_e32 v82, v82
	v_mul_f32_e32 v91, 0xbfb8aa3b, v91
	v_exp_f32_e32 v83, v83
	v_exp_f32_e32 v90, v90
	v_exp_f32_e32 v91, v91
	v_add_f32_e32 v88, 1.0, v88
	v_add_f32_e32 v89, 1.0, v89
	v_add_f32_e32 v94, 1.0, v94
	v_rcp_f32_e32 v88, v88
	v_add_f32_e32 v95, 1.0, v95
	v_rcp_f32_e32 v89, v89
	v_rcp_f32_e32 v94, v94
	v_rcp_f32_e32 v95, v95
	v_add_f32_e32 v82, 1.0, v82
	v_add_f32_e32 v83, 1.0, v83
	v_add_f32_e32 v90, 1.0, v90
	v_rcp_f32_e32 v82, v82
	v_add_f32_e32 v91, 1.0, v91
	v_rcp_f32_e32 v83, v83
	v_lshlrev_b32_e32 v100, 16, v143
	v_and_b32_e32 v101, 0xffff0000, v143
	v_rcp_f32_e32 v90, v90
	v_rcp_f32_e32 v91, v91
	v_lshlrev_b32_e32 v96, 16, v139
	v_and_b32_e32 v97, 0xffff0000, v139
	v_pk_mul_f32 v[88:89], v[88:89], v[100:101]
	v_pk_mul_f32 v[84:85], v[84:85], v[208:209] op_sel_hi:[1,0]
	v_pk_fma_f32 v[88:89], v[94:95], v[96:97], v[88:89]
	v_lshlrev_b32_e32 v96, 16, v144
	v_and_b32_e32 v97, 0xffff0000, v144
	v_lshlrev_b32_e32 v94, 16, v140
	v_and_b32_e32 v95, 0xffff0000, v140
	v_pk_mul_f32 v[82:83], v[82:83], v[96:97]
	v_pk_mul_f32 v[92:93], v[92:93], v[208:209] op_sel_hi:[1,0]
	v_pk_fma_f32 v[90:91], v[90:91], v[94:95], v[82:83]
	v_mul_f32_e32 v83, 0xbfb8aa3b, v84
	v_exp_f32_e32 v83, v83
	v_mul_f32_e32 v85, 0xbfb8aa3b, v85
	v_mul_f32_e32 v82, 0xbfb8aa3b, v92
	v_exp_f32_e32 v85, v85
	v_add_f32_e32 v83, 1.0, v83
	v_rcp_f32_e32 v84, v83
	v_mul_f32_e32 v83, 0xbfb8aa3b, v93
	v_exp_f32_e32 v82, v82
	v_exp_f32_e32 v83, v83
	v_add_f32_e32 v85, 1.0, v85
	v_pk_mul_f32 v[70:71], v[70:71], v[202:203] op_sel_hi:[1,0]
	v_add_f32_e32 v82, 1.0, v82
	v_add_f32_e32 v83, 1.0, v83
	v_rcp_f32_e32 v85, v85
	v_pk_mul_f32 v[78:79], v[78:79], v[202:203] op_sel_hi:[1,0]
	v_mul_f32_e32 v70, 0xbfb8aa3b, v70
	v_mul_f32_e32 v71, 0xbfb8aa3b, v71
	v_rcp_f32_e32 v82, v82
	v_rcp_f32_e32 v83, v83
	v_mul_f32_e32 v78, 0xbfb8aa3b, v78
	v_exp_f32_e32 v70, v70
	v_mul_f32_e32 v79, 0xbfb8aa3b, v79
	v_exp_f32_e32 v71, v71
	v_exp_f32_e32 v78, v78
	v_exp_f32_e32 v79, v79
	v_lshlrev_b32_e32 v94, 16, v145
	v_and_b32_e32 v95, 0xffff0000, v145
	v_lshlrev_b64 v[98:99], 11, v[204:205]
	v_lshlrev_b32_e32 v92, 16, v141
	v_and_b32_e32 v93, 0xffff0000, v141
	v_pk_mul_f32 v[84:85], v[84:85], v[94:95]
	v_add_f32_e32 v70, 1.0, v70
	v_pk_fma_f32 v[92:93], v[82:83], v[92:93], v[84:85]
	v_lshl_add_u64 v[82:83], s[40:41], 0, v[98:99]
	v_add_f32_e32 v71, 1.0, v71
	v_lshl_add_u64 v[82:83], v[82:83], 0, s[4:5]
	v_add_f32_e32 v78, 1.0, v78
	v_rcp_f32_e32 v70, v70
	v_add_f32_e32 v79, 1.0, v79
	v_rcp_f32_e32 v71, v71
	v_lshl_add_u64 v[82:83], v[82:83], 0, s[12:13]
	v_rcp_f32_e32 v78, v78
	v_rcp_f32_e32 v79, v79
	v_lshl_add_u64 v[94:95], v[82:83], 0, v[0:1]
	v_cvt_pk_bf16_f32 v82, v86, v87
	v_cvt_pk_bf16_f32 v83, v88, v89
	v_cvt_pk_bf16_f32 v84, v90, v91
	v_cvt_pk_bf16_f32 v85, v92, v93
	global_store_dwordx4 v[94:95], v[82:85], off sc1
	v_pk_mul_f32 v[72:73], v[72:73], v[202:203] op_sel_hi:[1,0]
	v_pk_mul_f32 v[80:81], v[80:81], v[202:203] op_sel_hi:[1,0]
	s_waitcnt vmcnt(3)
	v_lshlrev_b32_e32 v84, 16, v134
	v_and_b32_e32 v85, 0xffff0000, v134
	v_lshlrev_b32_e32 v82, 16, v130
	v_and_b32_e32 v83, 0xffff0000, v130
	v_pk_mul_f32 v[70:71], v[70:71], v[84:85]
	v_mul_f32_e32 v72, 0xbfb8aa3b, v72
	v_mul_f32_e32 v73, 0xbfb8aa3b, v73
	v_pk_mul_f32 v[66:67], v[66:67], v[202:203] op_sel_hi:[1,0]
	v_pk_fma_f32 v[70:71], v[78:79], v[82:83], v[70:71]
	v_mul_f32_e32 v78, 0xbfb8aa3b, v80
	v_exp_f32_e32 v72, v72
	v_mul_f32_e32 v79, 0xbfb8aa3b, v81
	v_exp_f32_e32 v73, v73
	v_pk_mul_f32 v[74:75], v[74:75], v[202:203] op_sel_hi:[1,0]
	v_exp_f32_e32 v78, v78
	v_exp_f32_e32 v79, v79
	v_mul_f32_e32 v66, 0xbfb8aa3b, v66
	v_mul_f32_e32 v67, 0xbfb8aa3b, v67
	v_mul_f32_e32 v74, 0xbfb8aa3b, v74
	v_exp_f32_e32 v66, v66
	v_mul_f32_e32 v75, 0xbfb8aa3b, v75
	v_exp_f32_e32 v67, v67
	v_exp_f32_e32 v74, v74
	v_exp_f32_e32 v75, v75
	v_add_f32_e32 v72, 1.0, v72
	v_add_f32_e32 v73, 1.0, v73
	v_add_f32_e32 v78, 1.0, v78
	v_rcp_f32_e32 v72, v72
	v_add_f32_e32 v79, 1.0, v79
	v_rcp_f32_e32 v73, v73
	v_rcp_f32_e32 v78, v78
	v_rcp_f32_e32 v79, v79
	v_add_f32_e32 v66, 1.0, v66
	v_add_f32_e32 v67, 1.0, v67
	v_add_f32_e32 v74, 1.0, v74
	v_rcp_f32_e32 v66, v66
	v_add_f32_e32 v75, 1.0, v75
	v_rcp_f32_e32 v67, v67
	v_lshlrev_b32_e32 v82, 16, v135
	v_and_b32_e32 v83, 0xffff0000, v135
	v_rcp_f32_e32 v74, v74
	v_rcp_f32_e32 v75, v75
	v_lshlrev_b32_e32 v80, 16, v131
	v_and_b32_e32 v81, 0xffff0000, v131
	v_pk_mul_f32 v[72:73], v[72:73], v[82:83]
	v_pk_mul_f32 v[68:69], v[68:69], v[202:203] op_sel_hi:[1,0]
	v_pk_fma_f32 v[72:73], v[78:79], v[80:81], v[72:73]
	v_lshlrev_b32_e32 v80, 16, v136
	v_and_b32_e32 v81, 0xffff0000, v136
	v_lshlrev_b32_e32 v78, 16, v132
	v_and_b32_e32 v79, 0xffff0000, v132
	v_pk_mul_f32 v[66:67], v[66:67], v[80:81]
	v_pk_mul_f32 v[76:77], v[76:77], v[202:203] op_sel_hi:[1,0]
	v_pk_fma_f32 v[74:75], v[74:75], v[78:79], v[66:67]
	v_mul_f32_e32 v67, 0xbfb8aa3b, v68
	v_exp_f32_e32 v67, v67
	v_mul_f32_e32 v69, 0xbfb8aa3b, v69
	v_mul_f32_e32 v66, 0xbfb8aa3b, v76
	v_exp_f32_e32 v69, v69
	v_add_f32_e32 v67, 1.0, v67
	v_rcp_f32_e32 v68, v67
	v_mul_f32_e32 v67, 0xbfb8aa3b, v77
; __device__ __forceinline__ float sigmoidf_(float x) { return __builtin_amdgcn_rcpf(1.0f + __builtin_amdgcn_exp2f(-1.4426950408889634f * x)); }
;     __device__ __forceinline__ void operator()(const f32x4 (&acc)[2][2][4][2], const Unit& u, int wr, int wc, int fr, int fq) const {
;     ...
;                 if (mode == EP_GATE) {
; #pragma unroll
;                     for (int m = 0; m < 4; ++m) { const size_t off = (size_t)(row0 + ai * HALF + m * 16) * DM + u.pn * 128 + wc * 32 + 8 * fq; yall[ai][m][0] = *(const u32x4*)(Y1 + off); yall[ai][m][1] = *(const u32x4*)(Y2 + off); }
;     ...
;                 if (mode == EP_GATE) {
;                     const size_t off = (size_t)row * DM + u.pn * 128 + wc * 32 + 8 * fq;
;                     const f32x4 a0 = acc[ai][0][m][0] * rs1, a1 = acc[ai][0][m][1] * rs1, b0 = acc[ai][1][m][0] * rs1, b1 = acc[ai][1][m][1] * rs1;
;                     const u32x4 y1 = yall[ai][m][0], y2 = yall[ai][m][1];
;                     f32x4 r0, r1;
;                     r0[0] = sigmoidf_(a0[0]) * bf_lo(y1.x) + sigmoidf_(b0[0]) * bf_lo(y2.x); r0[1] = sigmoidf_(a0[1]) * bf_hi(y1.x) + sigmoidf_(b0[1]) * bf_hi(y2.x);
;                     r0[2] = sigmoidf_(a0[2]) * bf_lo(y1.y) + sigmoidf_(b0[2]) * bf_lo(y2.y); r0[3] = sigmoidf_(a0[3]) * bf_hi(y1.y) + sigmoidf_(b0[3]) * bf_hi(y2.y);
;                     r1[0] = sigmoidf_(a1[0]) * bf_lo(y1.z) + sigmoidf_(b1[0]) * bf_lo(y2.z); r1[1] = sigmoidf_(a1[1]) * bf_hi(y1.z) + sigmoidf_(b1[1]) * bf_hi(y2.z);
;                     r1[2] = sigmoidf_(a1[2]) * bf_lo(y1.w) + sigmoidf_(b1[2]) * bf_lo(y2.w); r1[3] = sigmoidf_(a1[3]) * bf_hi(y1.w) + sigmoidf_(b1[3]) * bf_hi(y2.w);
;                     store8(O + off, r0, r1);
	v_exp_f32_e32 v66, v66
	v_exp_f32_e32 v67, v67
	v_add_f32_e32 v69, 1.0, v69
	v_rcp_f32_e32 v69, v69
	v_add_f32_e32 v66, 1.0, v66
	v_add_f32_e32 v67, 1.0, v67
	v_rcp_f32_e32 v66, v66
	v_rcp_f32_e32 v67, v67
	v_lshlrev_b32_e32 v78, 16, v137
	v_and_b32_e32 v79, 0xffff0000, v137
	v_lshlrev_b32_e32 v76, 16, v133
	v_and_b32_e32 v77, 0xffff0000, v133
	v_pk_mul_f32 v[68:69], v[68:69], v[78:79]
	v_pk_mul_f32 v[54:55], v[54:55], v[196:197] op_sel_hi:[1,0]
	v_pk_fma_f32 v[76:77], v[66:67], v[76:77], v[68:69]
	v_lshlrev_b64 v[66:67], 11, v[198:199]
	v_lshl_add_u64 v[66:67], s[40:41], 0, v[66:67]
	v_lshl_add_u64 v[66:67], v[66:67], 0, s[4:5]
	v_lshl_add_u64 v[66:67], v[66:67], 0, s[12:13]
	v_lshl_add_u64 v[78:79], v[66:67], 0, v[0:1]
	v_cvt_pk_bf16_f32 v66, v70, v71
	v_cvt_pk_bf16_f32 v67, v72, v73
	v_cvt_pk_bf16_f32 v68, v74, v75
	v_cvt_pk_bf16_f32 v69, v76, v77
	global_store_dwordx4 v[78:79], v[66:69], off sc1
	v_pk_mul_f32 v[62:63], v[62:63], v[196:197] op_sel_hi:[1,0]
	v_mul_f32_e32 v54, 0xbfb8aa3b, v54
	v_lshlrev_b64 v[66:67], 10, v[188:189]
	v_lshl_add_u64 v[66:67], v[66:67], 0, v[200:201]
	v_lshlrev_b64 v[66:67], 1, v[66:67]
	v_lshl_add_u64 v[68:69], s[38:39], 0, v[66:67]
	v_lshl_add_u64 v[66:67], s[42:43], 0, v[66:67]
	global_load_dwordx4 v[94:97], v[68:69], off
	global_load_dwordx4 v[90:93], v[66:67], off
	v_lshlrev_b64 v[66:67], 10, v[184:185]
	v_lshl_add_u64 v[66:67], v[66:67], 0, v[200:201]
	v_lshlrev_b64 v[66:67], 1, v[66:67]
	v_lshl_add_u64 v[68:69], s[38:39], 0, v[66:67]
	v_lshl_add_u64 v[66:67], s[42:43], 0, v[66:67]
	global_load_dwordx4 v[82:85], v[68:69], off
	global_load_dwordx4 v[86:89], v[66:67], off
	v_lshlrev_b64 v[66:67], 10, v[182:183]
	v_lshl_add_u64 v[66:67], v[66:67], 0, v[200:201]
	v_lshlrev_b64 v[66:67], 1, v[66:67]
	v_lshl_add_u64 v[68:69], s[38:39], 0, v[66:67]
	v_lshl_add_u64 v[66:67], s[42:43], 0, v[66:67]
	global_load_dwordx4 v[74:77], v[68:69], off
	global_load_dwordx4 v[78:81], v[66:67], off
	v_mul_f32_e32 v55, 0xbfb8aa3b, v55
	v_mul_f32_e32 v62, 0xbfb8aa3b, v62
	v_exp_f32_e32 v54, v54
	v_mul_f32_e32 v63, 0xbfb8aa3b, v63
	v_exp_f32_e32 v55, v55
	v_exp_f32_e32 v62, v62
	v_exp_f32_e32 v63, v63
	v_add_f32_e32 v54, 1.0, v54
	v_add_f32_e32 v55, 1.0, v55
	v_add_f32_e32 v62, 1.0, v62
	v_rcp_f32_e32 v54, v54
	v_add_f32_e32 v63, 1.0, v63
	v_rcp_f32_e32 v55, v55
	v_rcp_f32_e32 v62, v62
	v_rcp_f32_e32 v63, v63
	v_pk_mul_f32 v[56:57], v[56:57], v[196:197] op_sel_hi:[1,0]
	v_pk_mul_f32 v[64:65], v[64:65], v[196:197] op_sel_hi:[1,0]
	v_mul_f32_e32 v56, 0xbfb8aa3b, v56
	v_mul_f32_e32 v57, 0xbfb8aa3b, v57
	v_pk_mul_f32 v[50:51], v[50:51], v[196:197] op_sel_hi:[1,0]
	v_exp_f32_e32 v56, v56
	v_exp_f32_e32 v57, v57
	v_pk_mul_f32 v[58:59], v[58:59], v[196:197] op_sel_hi:[1,0]
	v_mul_f32_e32 v50, 0xbfb8aa3b, v50
	v_mul_f32_e32 v51, 0xbfb8aa3b, v51
	v_mul_f32_e32 v58, 0xbfb8aa3b, v58
	v_exp_f32_e32 v50, v50
	v_mul_f32_e32 v59, 0xbfb8aa3b, v59
	v_exp_f32_e32 v51, v51
	v_exp_f32_e32 v58, v58
	v_exp_f32_e32 v59, v59
	v_add_f32_e32 v56, 1.0, v56
	v_add_f32_e32 v57, 1.0, v57
	v_rcp_f32_e32 v56, v56
	v_rcp_f32_e32 v57, v57
	v_add_f32_e32 v50, 1.0, v50
	v_add_f32_e32 v51, 1.0, v51
	v_add_f32_e32 v58, 1.0, v58
	v_rcp_f32_e32 v50, v50
	v_add_f32_e32 v59, 1.0, v59
	v_rcp_f32_e32 v51, v51
	v_rcp_f32_e32 v58, v58
	v_rcp_f32_e32 v59, v59
	v_pk_mul_f32 v[52:53], v[52:53], v[196:197] op_sel_hi:[1,0]
	v_lshlrev_b64 v[66:67], 10, v[178:179]
	v_pk_mul_f32 v[60:61], v[60:61], v[196:197] op_sel_hi:[1,0]
	v_mul_f32_e32 v53, 0xbfb8aa3b, v53
	v_lshl_add_u64 v[66:67], v[66:67], 0, v[200:201]
	v_exp_f32_e32 v53, v53
	v_lshlrev_b64 v[70:71], 1, v[66:67]
	v_lshl_add_u64 v[66:67], s[38:39], 0, v[70:71]
	v_lshl_add_u64 v[70:71], s[42:43], 0, v[70:71]
	global_load_dwordx4 v[66:69], v[66:67], off
	v_add_f32_e32 v53, 1.0, v53
	global_load_dwordx4 v[70:73], v[70:71], off
	v_rcp_f32_e32 v53, v53
	v_pk_mul_f32 v[38:39], v[38:39], v[190:191] op_sel_hi:[1,0]
	v_pk_mul_f32 v[46:47], v[46:47], v[190:191] op_sel_hi:[1,0]
	v_mul_f32_e32 v38, 0xbfb8aa3b, v38
	v_mul_f32_e32 v39, 0xbfb8aa3b, v39
	v_mul_f32_e32 v46, 0xbfb8aa3b, v46
	v_exp_f32_e32 v38, v38
	v_mul_f32_e32 v47, 0xbfb8aa3b, v47
	v_exp_f32_e32 v39, v39
	s_waitcnt vmcnt(7)
	v_lshlrev_b32_e32 v98, 16, v94
	s_waitcnt vmcnt(6)
	v_lshlrev_b32_e32 v100, 16, v90
	v_and_b32_e32 v101, 0xffff0000, v90
	v_and_b32_e32 v99, 0xffff0000, v94
	v_pk_mul_f32 v[54:55], v[54:55], v[100:101]
	v_lshlrev_b32_e32 v90, 16, v91
	v_pk_fma_f32 v[54:55], v[62:63], v[98:99], v[54:55]
	v_mul_f32_e32 v62, 0xbfb8aa3b, v64
	v_mul_f32_e32 v63, 0xbfb8aa3b, v65
	v_exp_f32_e32 v62, v62
	v_exp_f32_e32 v63, v63
	v_and_b32_e32 v91, 0xffff0000, v91
	v_lshlrev_b32_e32 v64, 16, v95
	v_add_f32_e32 v62, 1.0, v62
	v_add_f32_e32 v63, 1.0, v63
	v_rcp_f32_e32 v62, v62
	v_rcp_f32_e32 v63, v63
	v_and_b32_e32 v65, 0xffff0000, v95
	v_pk_mul_f32 v[56:57], v[56:57], v[90:91]
	v_exp_f32_e32 v46, v46
	v_pk_fma_f32 v[56:57], v[62:63], v[64:65], v[56:57]
	v_lshlrev_b32_e32 v64, 16, v92
	v_and_b32_e32 v65, 0xffff0000, v92
	v_lshlrev_b32_e32 v62, 16, v96
	v_and_b32_e32 v63, 0xffff0000, v96
	v_pk_mul_f32 v[50:51], v[50:51], v[64:65]
	v_exp_f32_e32 v47, v47
	v_pk_fma_f32 v[58:59], v[58:59], v[62:63], v[50:51]
	v_mul_f32_e32 v51, 0xbfb8aa3b, v52
	v_exp_f32_e32 v51, v51
	v_mul_f32_e32 v50, 0xbfb8aa3b, v60
	v_exp_f32_e32 v50, v50
	v_lshlrev_b32_e32 v62, 16, v93
	v_add_f32_e32 v51, 1.0, v51
	v_rcp_f32_e32 v52, v51
	v_mul_f32_e32 v51, 0xbfb8aa3b, v61
	v_exp_f32_e32 v51, v51
	v_add_f32_e32 v50, 1.0, v50
	v_rcp_f32_e32 v50, v50
	v_and_b32_e32 v63, 0xffff0000, v93
	v_add_f32_e32 v51, 1.0, v51
	v_rcp_f32_e32 v51, v51
	v_lshlrev_b32_e32 v60, 16, v97
	v_and_b32_e32 v61, 0xffff0000, v97
	v_pk_mul_f32 v[52:53], v[52:53], v[62:63]
	v_add_f32_e32 v38, 1.0, v38
	v_pk_fma_f32 v[60:61], v[50:51], v[60:61], v[52:53]
	v_lshlrev_b64 v[50:51], 11, v[188:189]
	v_lshl_add_u64 v[50:51], s[40:41], 0, v[50:51]
	v_add_f32_e32 v39, 1.0, v39
	v_lshl_add_u64 v[50:51], v[50:51], 0, s[4:5]
	v_add_f32_e32 v46, 1.0, v46
	v_rcp_f32_e32 v38, v38
	v_add_f32_e32 v47, 1.0, v47
	v_rcp_f32_e32 v39, v39
	v_lshl_add_u64 v[50:51], v[50:51], 0, s[12:13]
	v_rcp_f32_e32 v46, v46
	v_rcp_f32_e32 v47, v47
	v_lshl_add_u64 v[62:63], v[50:51], 0, v[0:1]
	v_cvt_pk_bf16_f32 v50, v54, v55
	v_cvt_pk_bf16_f32 v51, v56, v57
	v_cvt_pk_bf16_f32 v52, v58, v59
	v_cvt_pk_bf16_f32 v53, v60, v61
	global_store_dwordx4 v[62:63], v[50:53], off sc1
	v_pk_mul_f32 v[40:41], v[40:41], v[190:191] op_sel_hi:[1,0]
	v_pk_mul_f32 v[48:49], v[48:49], v[190:191] op_sel_hi:[1,0]
	s_waitcnt vmcnt(5)
; __device__ __forceinline__ float sigmoidf_(float x) { return __builtin_amdgcn_rcpf(1.0f + __builtin_amdgcn_exp2f(-1.4426950408889634f * x)); }
;     __device__ __forceinline__ void operator()(const f32x4 (&acc)[2][2][4][2], const Unit& u, int wr, int wc, int fr, int fq) const {
;     ...
;                 if (mode == EP_GATE) {
;                     const size_t off = (size_t)row * DM + u.pn * 128 + wc * 32 + 8 * fq;
;                     const f32x4 a0 = acc[ai][0][m][0] * rs1, a1 = acc[ai][0][m][1] * rs1, b0 = acc[ai][1][m][0] * rs1, b1 = acc[ai][1][m][1] * rs1;
;                     const u32x4 y1 = yall[ai][m][0], y2 = yall[ai][m][1];
;                     f32x4 r0, r1;
;                     r0[0] = sigmoidf_(a0[0]) * bf_lo(y1.x) + sigmoidf_(b0[0]) * bf_lo(y2.x); r0[1] = sigmoidf_(a0[1]) * bf_hi(y1.x) + sigmoidf_(b0[1]) * bf_hi(y2.x);
;                     r0[2] = sigmoidf_(a0[2]) * bf_lo(y1.y) + sigmoidf_(b0[2]) * bf_lo(y2.y); r0[3] = sigmoidf_(a0[3]) * bf_hi(y1.y) + sigmoidf_(b0[3]) * bf_hi(y2.y);
;                     r1[0] = sigmoidf_(a1[0]) * bf_lo(y1.z) + sigmoidf_(b1[0]) * bf_lo(y2.z); r1[1] = sigmoidf_(a1[1]) * bf_hi(y1.z) + sigmoidf_(b1[1]) * bf_hi(y2.z);
;                     r1[2] = sigmoidf_(a1[2]) * bf_lo(y1.w) + sigmoidf_(b1[2]) * bf_lo(y2.w); r1[3] = sigmoidf_(a1[3]) * bf_hi(y1.w) + sigmoidf_(b1[3]) * bf_hi(y2.w);
	v_lshlrev_b32_e32 v52, 16, v86
	v_and_b32_e32 v53, 0xffff0000, v86
	v_lshlrev_b32_e32 v50, 16, v82
	v_and_b32_e32 v51, 0xffff0000, v82
	v_pk_mul_f32 v[38:39], v[38:39], v[52:53]
	v_mul_f32_e32 v40, 0xbfb8aa3b, v40
	v_mul_f32_e32 v41, 0xbfb8aa3b, v41
	v_pk_mul_f32 v[34:35], v[34:35], v[190:191] op_sel_hi:[1,0]
	v_pk_fma_f32 v[38:39], v[46:47], v[50:51], v[38:39]
	v_mul_f32_e32 v46, 0xbfb8aa3b, v48
	v_exp_f32_e32 v40, v40
	v_mul_f32_e32 v47, 0xbfb8aa3b, v49
	v_exp_f32_e32 v41, v41
	v_pk_mul_f32 v[42:43], v[42:43], v[190:191] op_sel_hi:[1,0]
	v_exp_f32_e32 v46, v46
	v_exp_f32_e32 v47, v47
	v_mul_f32_e32 v34, 0xbfb8aa3b, v34
	v_mul_f32_e32 v35, 0xbfb8aa3b, v35
	v_mul_f32_e32 v42, 0xbfb8aa3b, v42
	v_exp_f32_e32 v34, v34
	v_mul_f32_e32 v43, 0xbfb8aa3b, v43
	v_exp_f32_e32 v35, v35
	v_exp_f32_e32 v42, v42
	v_exp_f32_e32 v43, v43
	v_add_f32_e32 v40, 1.0, v40
	v_add_f32_e32 v41, 1.0, v41
	v_add_f32_e32 v46, 1.0, v46
	v_rcp_f32_e32 v40, v40
	v_add_f32_e32 v47, 1.0, v47
	v_rcp_f32_e32 v41, v41
	v_rcp_f32_e32 v46, v46
	v_rcp_f32_e32 v47, v47
	v_add_f32_e32 v34, 1.0, v34
	v_add_f32_e32 v35, 1.0, v35
	v_add_f32_e32 v42, 1.0, v42
	v_rcp_f32_e32 v34, v34
	v_add_f32_e32 v43, 1.0, v43
	v_rcp_f32_e32 v35, v35
	v_lshlrev_b32_e32 v50, 16, v87
	v_and_b32_e32 v51, 0xffff0000, v87
	v_rcp_f32_e32 v42, v42
	v_rcp_f32_e32 v43, v43
	v_lshlrev_b32_e32 v48, 16, v83
	v_and_b32_e32 v49, 0xffff0000, v83
	v_pk_mul_f32 v[40:41], v[40:41], v[50:51]
	v_pk_mul_f32 v[36:37], v[36:37], v[190:191] op_sel_hi:[1,0]
	v_pk_fma_f32 v[40:41], v[46:47], v[48:49], v[40:41]
	v_lshlrev_b32_e32 v48, 16, v88
	v_and_b32_e32 v49, 0xffff0000, v88
	v_lshlrev_b32_e32 v46, 16, v84
	v_and_b32_e32 v47, 0xffff0000, v84
	v_pk_mul_f32 v[34:35], v[34:35], v[48:49]
	v_pk_mul_f32 v[44:45], v[44:45], v[190:191] op_sel_hi:[1,0]
	v_pk_fma_f32 v[42:43], v[42:43], v[46:47], v[34:35]
	v_mul_f32_e32 v35, 0xbfb8aa3b, v36
	v_exp_f32_e32 v35, v35
	v_mul_f32_e32 v37, 0xbfb8aa3b, v37
	v_mul_f32_e32 v34, 0xbfb8aa3b, v44
	v_exp_f32_e32 v37, v37
	v_add_f32_e32 v35, 1.0, v35
	v_rcp_f32_e32 v36, v35
	v_mul_f32_e32 v35, 0xbfb8aa3b, v45
	v_exp_f32_e32 v34, v34
	v_exp_f32_e32 v35, v35
	v_add_f32_e32 v37, 1.0, v37
	v_pk_mul_f32 v[22:23], v[22:23], v[186:187] op_sel_hi:[1,0]
	v_add_f32_e32 v34, 1.0, v34
	v_add_f32_e32 v35, 1.0, v35
	v_rcp_f32_e32 v37, v37
	v_pk_mul_f32 v[30:31], v[30:31], v[186:187] op_sel_hi:[1,0]
	v_mul_f32_e32 v22, 0xbfb8aa3b, v22
	v_mul_f32_e32 v23, 0xbfb8aa3b, v23
	v_rcp_f32_e32 v34, v34
	v_rcp_f32_e32 v35, v35
	v_mul_f32_e32 v30, 0xbfb8aa3b, v30
	v_exp_f32_e32 v22, v22
	v_mul_f32_e32 v31, 0xbfb8aa3b, v31
	v_exp_f32_e32 v23, v23
	v_exp_f32_e32 v30, v30
	v_exp_f32_e32 v31, v31
	v_lshlrev_b32_e32 v46, 16, v89
	v_and_b32_e32 v47, 0xffff0000, v89
	v_lshlrev_b32_e32 v44, 16, v85
	v_and_b32_e32 v45, 0xffff0000, v85
	v_pk_mul_f32 v[36:37], v[36:37], v[46:47]
	v_add_f32_e32 v22, 1.0, v22
	v_pk_fma_f32 v[44:45], v[34:35], v[44:45], v[36:37]
	v_lshlrev_b64 v[34:35], 11, v[184:185]
	v_add_f32_e32 v23, 1.0, v23
	v_lshl_add_u64 v[34:35], s[40:41], 0, v[34:35]
	v_add_f32_e32 v30, 1.0, v30
	v_rcp_f32_e32 v22, v22
	v_add_f32_e32 v31, 1.0, v31
	v_rcp_f32_e32 v23, v23
	v_lshl_add_u64 v[34:35], v[34:35], 0, s[4:5]
	v_rcp_f32_e32 v30, v30
	v_rcp_f32_e32 v31, v31
	v_lshl_add_u64 v[34:35], v[34:35], 0, s[12:13]
	v_lshl_add_u64 v[46:47], v[34:35], 0, v[0:1]
	v_cvt_pk_bf16_f32 v34, v38, v39
	v_cvt_pk_bf16_f32 v35, v40, v41
	v_cvt_pk_bf16_f32 v36, v42, v43
	v_cvt_pk_bf16_f32 v37, v44, v45
	v_pk_mul_f32 v[24:25], v[24:25], v[186:187] op_sel_hi:[1,0]
	s_waitcnt vmcnt(3)
; __device__ __forceinline__ float sigmoidf_(float x) { return __builtin_amdgcn_rcpf(1.0f + __builtin_amdgcn_exp2f(-1.4426950408889634f * x)); }
; #define PG8_BAR __builtin_amdgcn_s_barrier()
;     __device__ __forceinline__ void operator()(const f32x4 (&acc)[2][2][4][2], const Unit& u, int wr, int wc, int fr, int fq) const {
;     ...
;                 if (mode == EP_GATE) {
;                     const size_t off = (size_t)row * DM + u.pn * 128 + wc * 32 + 8 * fq;
;                     const f32x4 a0 = acc[ai][0][m][0] * rs1, a1 = acc[ai][0][m][1] * rs1, b0 = acc[ai][1][m][0] * rs1, b1 = acc[ai][1][m][1] * rs1;
;                     const u32x4 y1 = yall[ai][m][0], y2 = yall[ai][m][1];
;                     f32x4 r0, r1;
;                     r0[0] = sigmoidf_(a0[0]) * bf_lo(y1.x) + sigmoidf_(b0[0]) * bf_lo(y2.x); r0[1] = sigmoidf_(a0[1]) * bf_hi(y1.x) + sigmoidf_(b0[1]) * bf_hi(y2.x);
;                     r0[2] = sigmoidf_(a0[2]) * bf_lo(y1.y) + sigmoidf_(b0[2]) * bf_lo(y2.y); r0[3] = sigmoidf_(a0[3]) * bf_hi(y1.y) + sigmoidf_(b0[3]) * bf_hi(y2.y);
;                     r1[0] = sigmoidf_(a1[0]) * bf_lo(y1.z) + sigmoidf_(b1[0]) * bf_lo(y2.z); r1[1] = sigmoidf_(a1[1]) * bf_hi(y1.z) + sigmoidf_(b1[1]) * bf_hi(y2.z);
;                     r1[2] = sigmoidf_(a1[2]) * bf_lo(y1.w) + sigmoidf_(b1[2]) * bf_lo(y2.w); r1[3] = sigmoidf_(a1[3]) * bf_hi(y1.w) + sigmoidf_(b1[3]) * bf_hi(y2.w);
;                     store8(O + off, r0, r1);
; template <class Epi, class Sched, bool ALIGN_EPI = false, bool SP2 = false>
; __device__ __forceinline__ void gemm_phase(PG8_LAS unsigned char* lds, const Gemm g, const Sched& S, const Epi& E, int wv) {
;     ...
;         if (!has_next) break;
; #pragma unroll
;         for (int a = 0; a < 2; ++a)
; #pragma unroll
;             for (int b = 0; b < 2; ++b)
; #pragma unroll
;                 for (int m = 0; m < 4; ++m)
; #pragma unroll
;                     for (int n = 0; n < 2; ++n) acc[a][b][m][n] = (f32x4){0.f, 0.f, 0.f, 0.f};
;         cur = nxt; cA = nA; cB = nB; ++ui;
;         if constexpr (ALIGN_EPI) { if (wr == 1) PG8_BAR; }
	v_lshlrev_b32_e32 v38, 16, v78
	v_and_b32_e32 v39, 0xffff0000, v78
	global_store_dwordx4 v[46:47], v[34:37], off sc1
	v_pk_mul_f32 v[32:33], v[32:33], v[186:187] op_sel_hi:[1,0]
	v_pk_mul_f32 v[22:23], v[22:23], v[38:39]
	v_lshlrev_b32_e32 v36, 16, v74
	v_and_b32_e32 v37, 0xffff0000, v74
	v_mul_f32_e32 v24, 0xbfb8aa3b, v24
	v_mul_f32_e32 v25, 0xbfb8aa3b, v25
	v_pk_mul_f32 v[18:19], v[18:19], v[186:187] op_sel_hi:[1,0]
	v_pk_fma_f32 v[22:23], v[30:31], v[36:37], v[22:23]
	v_mul_f32_e32 v30, 0xbfb8aa3b, v32
	v_exp_f32_e32 v24, v24
	v_mul_f32_e32 v31, 0xbfb8aa3b, v33
	v_exp_f32_e32 v25, v25
	v_pk_mul_f32 v[26:27], v[26:27], v[186:187] op_sel_hi:[1,0]
	v_exp_f32_e32 v30, v30
	v_exp_f32_e32 v31, v31
	v_mul_f32_e32 v18, 0xbfb8aa3b, v18
	v_mul_f32_e32 v19, 0xbfb8aa3b, v19
	v_mul_f32_e32 v26, 0xbfb8aa3b, v26
	v_exp_f32_e32 v18, v18
	v_mul_f32_e32 v27, 0xbfb8aa3b, v27
	v_exp_f32_e32 v19, v19
	v_exp_f32_e32 v26, v26
	v_exp_f32_e32 v27, v27
	v_add_f32_e32 v24, 1.0, v24
	v_add_f32_e32 v25, 1.0, v25
	v_add_f32_e32 v30, 1.0, v30
	v_rcp_f32_e32 v24, v24
	v_add_f32_e32 v31, 1.0, v31
	v_rcp_f32_e32 v25, v25
	v_rcp_f32_e32 v30, v30
	v_rcp_f32_e32 v31, v31
	v_add_f32_e32 v18, 1.0, v18
	v_add_f32_e32 v19, 1.0, v19
	v_add_f32_e32 v26, 1.0, v26
	v_rcp_f32_e32 v18, v18
	v_add_f32_e32 v27, 1.0, v27
	v_rcp_f32_e32 v19, v19
	v_lshlrev_b32_e32 v36, 16, v79
	v_and_b32_e32 v37, 0xffff0000, v79
	v_rcp_f32_e32 v26, v26
	v_rcp_f32_e32 v27, v27
	v_lshlrev_b32_e32 v32, 16, v75
	v_and_b32_e32 v33, 0xffff0000, v75
	v_pk_mul_f32 v[24:25], v[24:25], v[36:37]
	v_pk_mul_f32 v[20:21], v[20:21], v[186:187] op_sel_hi:[1,0]
	v_pk_fma_f32 v[24:25], v[30:31], v[32:33], v[24:25]
	v_lshlrev_b32_e32 v32, 16, v80
	v_and_b32_e32 v33, 0xffff0000, v80
	v_lshlrev_b32_e32 v30, 16, v76
	v_and_b32_e32 v31, 0xffff0000, v76
	v_pk_mul_f32 v[18:19], v[18:19], v[32:33]
	v_pk_mul_f32 v[28:29], v[28:29], v[186:187] op_sel_hi:[1,0]
	v_pk_fma_f32 v[26:27], v[26:27], v[30:31], v[18:19]
	v_mul_f32_e32 v19, 0xbfb8aa3b, v20
	v_exp_f32_e32 v19, v19
	v_mul_f32_e32 v21, 0xbfb8aa3b, v21
	v_mul_f32_e32 v18, 0xbfb8aa3b, v28
	v_exp_f32_e32 v21, v21
	v_add_f32_e32 v19, 1.0, v19
	v_rcp_f32_e32 v20, v19
	v_mul_f32_e32 v19, 0xbfb8aa3b, v29
	v_exp_f32_e32 v18, v18
	v_exp_f32_e32 v19, v19
	v_add_f32_e32 v21, 1.0, v21
	v_pk_mul_f32 v[6:7], v[6:7], v[180:181] op_sel_hi:[1,0]
	v_add_f32_e32 v18, 1.0, v18
	v_add_f32_e32 v19, 1.0, v19
	v_rcp_f32_e32 v21, v21
	v_pk_mul_f32 v[14:15], v[14:15], v[180:181] op_sel_hi:[1,0]
	v_mul_f32_e32 v6, 0xbfb8aa3b, v6
	v_mul_f32_e32 v7, 0xbfb8aa3b, v7
	v_rcp_f32_e32 v18, v18
	v_rcp_f32_e32 v19, v19
	v_mul_f32_e32 v14, 0xbfb8aa3b, v14
	v_exp_f32_e32 v6, v6
	v_mul_f32_e32 v15, 0xbfb8aa3b, v15
	v_exp_f32_e32 v7, v7
	v_exp_f32_e32 v14, v14
	v_exp_f32_e32 v15, v15
	v_lshlrev_b32_e32 v30, 16, v81
	v_and_b32_e32 v31, 0xffff0000, v81
	v_lshlrev_b64 v[34:35], 11, v[182:183]
	v_lshlrev_b32_e32 v28, 16, v77
	v_and_b32_e32 v29, 0xffff0000, v77
	v_pk_mul_f32 v[20:21], v[20:21], v[30:31]
	v_add_f32_e32 v6, 1.0, v6
	v_pk_fma_f32 v[28:29], v[18:19], v[28:29], v[20:21]
	v_lshl_add_u64 v[18:19], s[40:41], 0, v[34:35]
	v_add_f32_e32 v7, 1.0, v7
	v_lshl_add_u64 v[18:19], v[18:19], 0, s[4:5]
	v_add_f32_e32 v14, 1.0, v14
	v_rcp_f32_e32 v6, v6
	v_add_f32_e32 v15, 1.0, v15
	v_rcp_f32_e32 v7, v7
	v_lshl_add_u64 v[18:19], v[18:19], 0, s[12:13]
	v_rcp_f32_e32 v14, v14
	v_rcp_f32_e32 v15, v15
	v_lshl_add_u64 v[30:31], v[18:19], 0, v[0:1]
	v_cvt_pk_bf16_f32 v18, v22, v23
	v_cvt_pk_bf16_f32 v19, v24, v25
	v_cvt_pk_bf16_f32 v20, v26, v27
	v_cvt_pk_bf16_f32 v21, v28, v29
	global_store_dwordx4 v[30:31], v[18:21], off sc1
	v_pk_mul_f32 v[8:9], v[8:9], v[180:181] op_sel_hi:[1,0]
	v_pk_mul_f32 v[16:17], v[16:17], v[180:181] op_sel_hi:[1,0]
	s_waitcnt vmcnt(3)
	v_lshlrev_b32_e32 v20, 16, v70
	v_and_b32_e32 v21, 0xffff0000, v70
	v_lshlrev_b32_e32 v18, 16, v66
	v_and_b32_e32 v19, 0xffff0000, v66
	v_pk_mul_f32 v[6:7], v[6:7], v[20:21]
	v_mul_f32_e32 v8, 0xbfb8aa3b, v8
	v_mul_f32_e32 v9, 0xbfb8aa3b, v9
	v_pk_mul_f32 v[2:3], v[2:3], v[180:181] op_sel_hi:[1,0]
	v_pk_fma_f32 v[6:7], v[14:15], v[18:19], v[6:7]
	v_mul_f32_e32 v14, 0xbfb8aa3b, v16
	v_exp_f32_e32 v8, v8
	v_mul_f32_e32 v15, 0xbfb8aa3b, v17
	v_exp_f32_e32 v9, v9
	v_pk_mul_f32 v[10:11], v[10:11], v[180:181] op_sel_hi:[1,0]
	v_exp_f32_e32 v14, v14
	v_exp_f32_e32 v15, v15
	v_mul_f32_e32 v2, 0xbfb8aa3b, v2
	v_mul_f32_e32 v3, 0xbfb8aa3b, v3
	v_mul_f32_e32 v10, 0xbfb8aa3b, v10
	v_exp_f32_e32 v2, v2
	v_mul_f32_e32 v11, 0xbfb8aa3b, v11
	v_exp_f32_e32 v3, v3
	v_exp_f32_e32 v10, v10
	v_exp_f32_e32 v11, v11
	v_add_f32_e32 v8, 1.0, v8
	v_add_f32_e32 v9, 1.0, v9
	v_add_f32_e32 v14, 1.0, v14
	v_rcp_f32_e32 v8, v8
	v_add_f32_e32 v15, 1.0, v15
	v_rcp_f32_e32 v9, v9
	v_rcp_f32_e32 v14, v14
	v_rcp_f32_e32 v15, v15
	v_add_f32_e32 v2, 1.0, v2
	v_add_f32_e32 v3, 1.0, v3
	v_add_f32_e32 v10, 1.0, v10
	v_rcp_f32_e32 v2, v2
	v_add_f32_e32 v11, 1.0, v11
	v_rcp_f32_e32 v3, v3
	v_lshlrev_b32_e32 v18, 16, v71
	v_and_b32_e32 v19, 0xffff0000, v71
	v_rcp_f32_e32 v10, v10
	v_rcp_f32_e32 v11, v11
	v_lshlrev_b32_e32 v16, 16, v67
	v_and_b32_e32 v17, 0xffff0000, v67
	v_pk_mul_f32 v[8:9], v[8:9], v[18:19]
	v_pk_mul_f32 v[4:5], v[4:5], v[180:181] op_sel_hi:[1,0]
	v_pk_fma_f32 v[8:9], v[14:15], v[16:17], v[8:9]
	v_lshlrev_b32_e32 v16, 16, v72
	v_and_b32_e32 v17, 0xffff0000, v72
	v_lshlrev_b32_e32 v14, 16, v68
	v_and_b32_e32 v15, 0xffff0000, v68
	v_pk_mul_f32 v[2:3], v[2:3], v[16:17]
	v_pk_mul_f32 v[12:13], v[12:13], v[180:181] op_sel_hi:[1,0]
	v_pk_fma_f32 v[10:11], v[10:11], v[14:15], v[2:3]
	v_mul_f32_e32 v3, 0xbfb8aa3b, v4
	v_exp_f32_e32 v3, v3
	v_mul_f32_e32 v5, 0xbfb8aa3b, v5
	v_mul_f32_e32 v2, 0xbfb8aa3b, v12
	v_exp_f32_e32 v5, v5
	v_add_f32_e32 v3, 1.0, v3
	v_rcp_f32_e32 v4, v3
	v_mul_f32_e32 v3, 0xbfb8aa3b, v13
	v_exp_f32_e32 v2, v2
	v_exp_f32_e32 v3, v3
	v_add_f32_e32 v5, 1.0, v5
	v_rcp_f32_e32 v5, v5
	v_add_f32_e32 v2, 1.0, v2
	v_add_f32_e32 v3, 1.0, v3
	v_rcp_f32_e32 v2, v2
	v_rcp_f32_e32 v3, v3
	v_lshlrev_b32_e32 v14, 16, v73
	v_and_b32_e32 v15, 0xffff0000, v73
	v_lshlrev_b32_e32 v12, 16, v69
	v_and_b32_e32 v13, 0xffff0000, v69
	v_pk_mul_f32 v[4:5], v[4:5], v[14:15]
	v_mov_b32_e32 v195, 0x3727c5ac
	v_pk_fma_f32 v[12:13], v[2:3], v[12:13], v[4:5]
	v_lshlrev_b64 v[2:3], 11, v[178:179]
	v_lshl_add_u64 v[2:3], s[40:41], 0, v[2:3]
	v_lshl_add_u64 v[2:3], v[2:3], 0, s[4:5]
	v_lshl_add_u64 v[2:3], v[2:3], 0, s[12:13]
	v_lshl_add_u64 v[14:15], v[2:3], 0, v[0:1]
	v_cvt_pk_bf16_f32 v2, v6, v7
	v_cvt_pk_bf16_f32 v3, v8, v9
	v_cvt_pk_bf16_f32 v4, v10, v11
	v_cvt_pk_bf16_f32 v5, v12, v13
	s_mov_b64 s[4:5], -1
	global_store_dwordx4 v[14:15], v[2:5], off sc1
	s_cbranch_vccnz .LBB0_1075
	s_andn2_b64 vcc, exec, s[0:1]
	s_cbranch_vccnz .LBB0_1074
	s_barrier
	s_branch .LBB0_1074

;     __device__ __forceinline__ void operator()(const f32x4 (&acc)[2][2][4][2], const Unit& u, int wr, int wc, int fr, int fq) const {
;     ...
;                     } else {
;                         const size_t off = (size_t)row * DM + col8;
;                         const u32x4 xi = yall[ai][m][bj];
;                         const f32x4 x0 = (f32x4){bf_lo(xi.x), bf_hi(xi.x), bf_lo(xi.y), bf_hi(xi.y)} + v0, x1 = (f32x4){bf_lo(xi.z), bf_hi(xi.z), bf_lo(xi.w), bf_hi(xi.w)} + v1;
;                         store8(xb + off, x0, x1);
;                         ssacc += (x0[0] * x0[0] + x0[1] * x0[1]) + (x0[2] * x0[2] + x0[3] * x0[3]) + (x1[0] * x1[0] + x1[1] * x1[1]) + (x1[2] * x1[2] + x1[3] * x1[3]);
;                     }
;                 }
;                 if (mode == EP_RESID) {
;                     ssacc += __shfl_xor(ssacc, 16); ssacc += __shfl_xor(ssacc, 32);
;                     if (fq == 0) ss_out[(size_t)row * 16 + u.pn * 4 + wc] = ssacc;
;                 }
.LBB0_1150:
	v_lshl_add_u32 v174, s12, 8, v188
	s_lshl_b32 s28, s54, 8
	s_ashr_i32 s29, s28, 31
	v_ashrrev_i32_e32 v175, 31, v174
	v_lshl_add_u64 v[172:173], s[28:29], 1, v[164:165]
	v_lshlrev_b64 v[192:193], 11, v[174:175]
	v_lshl_add_u64 v[130:131], v[172:173], 0, v[192:193]
	global_load_dwordx4 v[196:199], v[130:131], off
	global_load_dwordx4 v[154:157], v[130:131], off offset:256
	v_or_b32_e32 v184, 16, v174
	v_ashrrev_i32_e32 v185, 31, v184
	v_or_b32_e32 v178, 32, v174
	v_lshlrev_b64 v[186:187], 11, v[184:185]
	v_ashrrev_i32_e32 v179, 31, v178
	v_or_b32_e32 v176, 48, v174
	v_lshl_add_u64 v[130:131], v[172:173], 0, v[186:187]
	v_lshlrev_b64 v[182:183], 11, v[178:179]
	v_ashrrev_i32_e32 v177, 31, v176
	global_load_dwordx4 v[150:153], v[130:131], off
	global_load_dwordx4 v[146:149], v[130:131], off offset:256
	v_lshl_add_u64 v[130:131], v[172:173], 0, v[182:183]
	v_lshlrev_b64 v[180:181], 11, v[176:177]
	global_load_dwordx4 v[142:145], v[130:131], off
	global_load_dwordx4 v[138:141], v[130:131], off offset:256
	v_lshl_add_u64 v[130:131], v[172:173], 0, v[180:181]
	global_load_dwordx4 v[134:137], v[130:131], off
	s_nop 0
	global_load_dwordx4 v[130:133], v[130:131], off offset:256
	v_or_b32_e32 v170, s28, v190
	v_ashrrev_i32_e32 v171, 31, v170
	s_waitcnt vmcnt(0)
	v_lshlrev_b32_e32 v200, 16, v196
	v_and_b32_e32 v201, 0xffff0000, v196
	v_lshlrev_b32_e32 v196, 16, v197
	v_and_b32_e32 v197, 0xffff0000, v197
	v_pk_add_f32 v[128:129], v[128:129], v[196:197]
	v_lshlrev_b32_e32 v196, 16, v198
	v_and_b32_e32 v197, 0xffff0000, v198
	v_lshlrev_b32_e32 v198, 16, v199
	v_and_b32_e32 v199, 0xffff0000, v199
	v_pk_add_f32 v[126:127], v[126:127], v[200:201]
	v_pk_add_f32 v[198:199], v[124:125], v[198:199]
	v_pk_add_f32 v[196:197], v[122:123], v[196:197]
	v_lshl_add_u64 v[122:123], s[6:7], 0, v[192:193]
	v_lshl_add_u64 v[192:193], v[170:171], 1, v[122:123]
	v_cvt_pk_bf16_f32 v122, v126, v127
	v_cvt_pk_bf16_f32 v123, v128, v129
	v_cvt_pk_bf16_f32 v124, v196, v197
	v_cvt_pk_bf16_f32 v125, v198, v199
	global_store_dwordx4 v[192:193], v[122:125], off sc1
	s_nop 1
	v_mul_f32_e32 v122, v127, v127
	v_mul_f32_e32 v123, v129, v129
	v_fmac_f32_e32 v122, v126, v126
	v_fmac_f32_e32 v123, v128, v128
	v_add_f32_e32 v122, v122, v123
	v_mul_f32_e32 v123, v197, v197
	v_fmac_f32_e32 v123, v196, v196
	v_add_f32_e32 v122, v123, v122
	v_mul_f32_e32 v123, v199, v199
	v_fmac_f32_e32 v123, v198, v198
	v_add_f32_e32 v126, v123, v122
	v_lshlrev_b32_e32 v122, 16, v154
	v_and_b32_e32 v123, 0xffff0000, v154
	v_lshlrev_b32_e32 v124, 16, v155
	v_and_b32_e32 v125, 0xffff0000, v155
	v_pk_add_f32 v[120:121], v[120:121], v[124:125]
	v_pk_add_f32 v[118:119], v[118:119], v[122:123]
	v_lshlrev_b32_e32 v122, 16, v156
	v_and_b32_e32 v123, 0xffff0000, v156
	v_lshlrev_b32_e32 v124, 16, v157
	v_and_b32_e32 v125, 0xffff0000, v157
	v_pk_add_f32 v[124:125], v[116:117], v[124:125]
	v_pk_add_f32 v[122:123], v[114:115], v[122:123]
	v_cvt_pk_bf16_f32 v114, v118, v119
	v_cvt_pk_bf16_f32 v115, v120, v121
	v_cvt_pk_bf16_f32 v116, v122, v123
	v_cvt_pk_bf16_f32 v117, v124, v125
	global_store_dwordx4 v[192:193], v[114:117], off offset:256 sc1
	s_nop 1
	v_mul_f32_e32 v114, v119, v119
	v_mul_f32_e32 v115, v121, v121
	v_fmac_f32_e32 v114, v118, v118
	v_fmac_f32_e32 v115, v120, v120
	v_add_f32_e32 v114, v114, v115
	v_mul_f32_e32 v115, v123, v123
	v_fmac_f32_e32 v115, v122, v122
	v_add_f32_e32 v114, v115, v114
	v_mul_f32_e32 v115, v125, v125
	v_fmac_f32_e32 v115, v124, v124
	v_add_f32_e32 v114, v115, v114
	v_add_f32_e32 v114, v126, v114
	ds_bpermute_b32 v115, v216, v114
	s_waitcnt lgkmcnt(0)
	v_add_f32_e32 v114, v114, v115
	ds_bpermute_b32 v115, v217, v114
	s_and_saveexec_b64 s[16:17], s[0:1]
	s_cbranch_execz .LBB0_1152
	s_waitcnt lgkmcnt(0)
	v_add_f32_e32 v116, v114, v115
	s_lshl_b32 s28, s54, 2
	v_lshlrev_b64 v[114:115], 6, v[174:175]
	s_ashr_i32 s29, s28, 31
	v_lshl_add_u64 v[114:115], s[8:9], 0, v[114:115]
	v_lshl_add_u64 v[114:115], s[28:29], 2, v[114:115]
	s_lshl_b32 s12, s50, 2
	v_lshl_add_u64 v[114:115], v[114:115], 0, s[12:13]
	global_store_dword v[114:115], v116, off
.LBB0_1152:
	s_or_b64 exec, exec, s[16:17]
	v_lshlrev_b32_e32 v114, 16, v150
	s_waitcnt lgkmcnt(0)
	v_and_b32_e32 v115, 0xffff0000, v150
	v_lshlrev_b32_e32 v116, 16, v151
	v_and_b32_e32 v117, 0xffff0000, v151
	v_pk_add_f32 v[112:113], v[112:113], v[116:117]
	v_pk_add_f32 v[110:111], v[110:111], v[114:115]
	v_lshlrev_b32_e32 v114, 16, v152
	v_and_b32_e32 v115, 0xffff0000, v152
	v_lshlrev_b32_e32 v116, 16, v153
	v_and_b32_e32 v117, 0xffff0000, v153
	v_pk_add_f32 v[116:117], v[108:109], v[116:117]
	v_pk_add_f32 v[108:109], v[106:107], v[114:115]
	v_lshl_add_u64 v[106:107], s[6:7], 0, v[186:187]
	v_lshl_add_u64 v[114:115], v[170:171], 1, v[106:107]
	v_cvt_pk_bf16_f32 v106, v110, v111
	v_mul_f32_e32 v111, v111, v111
	v_fmac_f32_e32 v111, v110, v110
	v_mul_f32_e32 v110, v113, v113
	v_fmac_f32_e32 v110, v112, v112
	v_add_f32_e32 v110, v111, v110
	v_mul_f32_e32 v111, v109, v109
	v_fmac_f32_e32 v111, v108, v108
	v_add_f32_e32 v110, v111, v110
	v_mul_f32_e32 v111, v117, v117
	v_fmac_f32_e32 v111, v116, v116
	v_cvt_pk_bf16_f32 v107, v112, v113
	v_add_f32_e32 v118, v111, v110
	v_lshlrev_b32_e32 v110, 16, v146
	v_and_b32_e32 v111, 0xffff0000, v146
	v_lshlrev_b32_e32 v112, 16, v147
	v_and_b32_e32 v113, 0xffff0000, v147
	v_pk_add_f32 v[104:105], v[104:105], v[112:113]
	v_pk_add_f32 v[102:103], v[102:103], v[110:111]
	v_lshlrev_b32_e32 v110, 16, v148
	v_and_b32_e32 v111, 0xffff0000, v148
	v_pk_add_f32 v[110:111], v[98:99], v[110:111]
	v_mul_f32_e32 v98, v103, v103
	v_mul_f32_e32 v99, v105, v105
	v_fmac_f32_e32 v98, v102, v102
	v_fmac_f32_e32 v99, v104, v104
	v_lshlrev_b32_e32 v112, 16, v149
	v_and_b32_e32 v113, 0xffff0000, v149
	v_add_f32_e32 v98, v98, v99
	v_mul_f32_e32 v99, v111, v111
	v_pk_add_f32 v[112:113], v[100:101], v[112:113]
	v_fmac_f32_e32 v99, v110, v110
	v_add_f32_e32 v98, v99, v98
	v_mul_f32_e32 v99, v113, v113
	v_fmac_f32_e32 v99, v112, v112
	v_add_f32_e32 v98, v99, v98
	v_add_f32_e32 v98, v118, v98
	ds_bpermute_b32 v99, v216, v98
	v_cvt_pk_bf16_f32 v108, v108, v109
	v_cvt_pk_bf16_f32 v109, v116, v117
	v_cvt_pk_bf16_f32 v100, v102, v103
	v_cvt_pk_bf16_f32 v101, v104, v105
	s_waitcnt lgkmcnt(0)
	v_add_f32_e32 v98, v98, v99
	ds_bpermute_b32 v99, v217, v98
	v_cvt_pk_bf16_f32 v102, v110, v111
	v_cvt_pk_bf16_f32 v103, v112, v113
	global_store_dwordx4 v[114:115], v[106:109], off sc1
	global_store_dwordx4 v[114:115], v[100:103], off offset:256 sc1
	s_and_saveexec_b64 s[16:17], s[0:1]
	s_cbranch_execz .LBB0_1154
	s_waitcnt lgkmcnt(0)
	v_add_f32_e32 v100, v98, v99
	s_lshl_b32 s28, s54, 2
	v_lshlrev_b64 v[98:99], 6, v[184:185]
	s_ashr_i32 s29, s28, 31
	v_lshl_add_u64 v[98:99], s[8:9], 0, v[98:99]
	v_lshl_add_u64 v[98:99], s[28:29], 2, v[98:99]
	s_lshl_b32 s12, s50, 2
	v_lshl_add_u64 v[98:99], v[98:99], 0, s[12:13]
	global_store_dword v[98:99], v100, off
;     __device__ __forceinline__ void operator()(const f32x4 (&acc)[2][2][4][2], const Unit& u, int wr, int wc, int fr, int fq) const {
;     ...
;                         const size_t off = (size_t)row * DM + col8;
;                         const u32x4 xi = yall[ai][m][bj];
;                         const f32x4 x0 = (f32x4){bf_lo(xi.x), bf_hi(xi.x), bf_lo(xi.y), bf_hi(xi.y)} + v0, x1 = (f32x4){bf_lo(xi.z), bf_hi(xi.z), bf_lo(xi.w), bf_hi(xi.w)} + v1;
;                         store8(xb + off, x0, x1);
;                         ssacc += (x0[0] * x0[0] + x0[1] * x0[1]) + (x0[2] * x0[2] + x0[3] * x0[3]) + (x1[0] * x1[0] + x1[1] * x1[1]) + (x1[2] * x1[2] + x1[3] * x1[3]);
;                     }
;                 }
;                 if (mode == EP_RESID) {
;                     ssacc += __shfl_xor(ssacc, 16); ssacc += __shfl_xor(ssacc, 32);
;                     if (fq == 0) ss_out[(size_t)row * 16 + u.pn * 4 + wc] = ssacc;
;                 }
.LBB0_1154:
	s_or_b64 exec, exec, s[16:17]
	v_lshlrev_b32_e32 v98, 16, v142
	s_waitcnt lgkmcnt(0)
	v_and_b32_e32 v99, 0xffff0000, v142
	v_lshlrev_b32_e32 v100, 16, v143
	v_and_b32_e32 v101, 0xffff0000, v143
	v_pk_add_f32 v[96:97], v[96:97], v[100:101]
	v_pk_add_f32 v[94:95], v[94:95], v[98:99]
	v_lshlrev_b32_e32 v98, 16, v144
	v_and_b32_e32 v99, 0xffff0000, v144
	v_lshlrev_b32_e32 v100, 16, v145
	v_and_b32_e32 v101, 0xffff0000, v145
	v_pk_add_f32 v[100:101], v[92:93], v[100:101]
	v_pk_add_f32 v[92:93], v[90:91], v[98:99]
	v_lshl_add_u64 v[90:91], s[6:7], 0, v[182:183]
	v_lshl_add_u64 v[98:99], v[170:171], 1, v[90:91]
	v_cvt_pk_bf16_f32 v90, v94, v95
	v_mul_f32_e32 v95, v95, v95
	v_fmac_f32_e32 v95, v94, v94
	v_mul_f32_e32 v94, v97, v97
	v_fmac_f32_e32 v94, v96, v96
	v_add_f32_e32 v94, v95, v94
	v_mul_f32_e32 v95, v93, v93
	v_fmac_f32_e32 v95, v92, v92
	v_add_f32_e32 v94, v95, v94
	v_mul_f32_e32 v95, v101, v101
	v_fmac_f32_e32 v95, v100, v100
	v_cvt_pk_bf16_f32 v91, v96, v97
	v_add_f32_e32 v102, v95, v94
	v_lshlrev_b32_e32 v94, 16, v138
	v_and_b32_e32 v95, 0xffff0000, v138
	v_lshlrev_b32_e32 v96, 16, v139
	v_and_b32_e32 v97, 0xffff0000, v139
	v_pk_add_f32 v[88:89], v[88:89], v[96:97]
	v_pk_add_f32 v[86:87], v[86:87], v[94:95]
	v_lshlrev_b32_e32 v94, 16, v140
	v_and_b32_e32 v95, 0xffff0000, v140
	v_pk_add_f32 v[94:95], v[82:83], v[94:95]
	v_mul_f32_e32 v82, v87, v87
	v_mul_f32_e32 v83, v89, v89
	v_fmac_f32_e32 v82, v86, v86
	v_fmac_f32_e32 v83, v88, v88
	v_lshlrev_b32_e32 v96, 16, v141
	v_and_b32_e32 v97, 0xffff0000, v141
	v_add_f32_e32 v82, v82, v83
	v_mul_f32_e32 v83, v95, v95
	v_pk_add_f32 v[96:97], v[84:85], v[96:97]
	v_fmac_f32_e32 v83, v94, v94
	v_add_f32_e32 v82, v83, v82
	v_mul_f32_e32 v83, v97, v97
	v_fmac_f32_e32 v83, v96, v96
	v_add_f32_e32 v82, v83, v82
	v_add_f32_e32 v82, v102, v82
	ds_bpermute_b32 v83, v216, v82
	v_cvt_pk_bf16_f32 v92, v92, v93
	v_cvt_pk_bf16_f32 v93, v100, v101
	v_cvt_pk_bf16_f32 v84, v86, v87
	v_cvt_pk_bf16_f32 v85, v88, v89
	s_waitcnt lgkmcnt(0)
	v_add_f32_e32 v82, v82, v83
	ds_bpermute_b32 v83, v217, v82
	v_cvt_pk_bf16_f32 v86, v94, v95
	v_cvt_pk_bf16_f32 v87, v96, v97
	global_store_dwordx4 v[98:99], v[90:93], off sc1
	global_store_dwordx4 v[98:99], v[84:87], off offset:256 sc1
	s_and_saveexec_b64 s[16:17], s[0:1]
	s_cbranch_execz .LBB0_1156
	s_waitcnt lgkmcnt(0)
	v_add_f32_e32 v84, v82, v83
	s_lshl_b32 s28, s54, 2
	v_lshlrev_b64 v[82:83], 6, v[178:179]
	s_ashr_i32 s29, s28, 31
	v_lshl_add_u64 v[82:83], s[8:9], 0, v[82:83]
	v_lshl_add_u64 v[82:83], s[28:29], 2, v[82:83]
	s_lshl_b32 s12, s50, 2
	v_lshl_add_u64 v[82:83], v[82:83], 0, s[12:13]
	global_store_dword v[82:83], v84, off
.LBB0_1156:
	s_or_b64 exec, exec, s[16:17]
	v_lshlrev_b32_e32 v82, 16, v134
	s_waitcnt lgkmcnt(0)
	v_and_b32_e32 v83, 0xffff0000, v134
	v_lshlrev_b32_e32 v84, 16, v135
	v_and_b32_e32 v85, 0xffff0000, v135
	v_pk_add_f32 v[80:81], v[80:81], v[84:85]
	v_pk_add_f32 v[78:79], v[78:79], v[82:83]
	v_lshlrev_b32_e32 v82, 16, v136
	v_and_b32_e32 v83, 0xffff0000, v136
	v_lshlrev_b32_e32 v84, 16, v137
	v_and_b32_e32 v85, 0xffff0000, v137
	v_pk_add_f32 v[84:85], v[76:77], v[84:85]
	v_pk_add_f32 v[76:77], v[74:75], v[82:83]
	v_lshl_add_u64 v[74:75], s[6:7], 0, v[180:181]
	v_lshl_add_u64 v[82:83], v[170:171], 1, v[74:75]
	v_cvt_pk_bf16_f32 v74, v78, v79
	v_mul_f32_e32 v79, v79, v79
	v_fmac_f32_e32 v79, v78, v78
	v_mul_f32_e32 v78, v81, v81
	v_fmac_f32_e32 v78, v80, v80
	v_add_f32_e32 v78, v79, v78
	v_mul_f32_e32 v79, v77, v77
	v_fmac_f32_e32 v79, v76, v76
	v_add_f32_e32 v78, v79, v78
	v_mul_f32_e32 v79, v85, v85
	v_fmac_f32_e32 v79, v84, v84
	v_cvt_pk_bf16_f32 v75, v80, v81
	v_add_f32_e32 v86, v79, v78
	v_lshlrev_b32_e32 v78, 16, v130
	v_and_b32_e32 v79, 0xffff0000, v130
	v_lshlrev_b32_e32 v80, 16, v131
	v_and_b32_e32 v81, 0xffff0000, v131
	v_pk_add_f32 v[72:73], v[72:73], v[80:81]
	v_pk_add_f32 v[70:71], v[70:71], v[78:79]
	v_lshlrev_b32_e32 v78, 16, v132
	v_and_b32_e32 v79, 0xffff0000, v132
	v_pk_add_f32 v[78:79], v[66:67], v[78:79]
	v_mul_f32_e32 v66, v71, v71
	v_mul_f32_e32 v67, v73, v73
	v_fmac_f32_e32 v66, v70, v70
	v_fmac_f32_e32 v67, v72, v72
	v_lshlrev_b32_e32 v80, 16, v133
	v_and_b32_e32 v81, 0xffff0000, v133
	v_add_f32_e32 v66, v66, v67
	v_mul_f32_e32 v67, v79, v79
	v_pk_add_f32 v[80:81], v[68:69], v[80:81]
	v_fmac_f32_e32 v67, v78, v78
	v_add_f32_e32 v66, v67, v66
	v_mul_f32_e32 v67, v81, v81
	v_fmac_f32_e32 v67, v80, v80
	v_add_f32_e32 v66, v67, v66
	v_add_f32_e32 v66, v86, v66
	ds_bpermute_b32 v67, v216, v66
	v_cvt_pk_bf16_f32 v76, v76, v77
	v_cvt_pk_bf16_f32 v77, v84, v85
	v_cvt_pk_bf16_f32 v68, v70, v71
	v_cvt_pk_bf16_f32 v69, v72, v73
	s_waitcnt lgkmcnt(0)
	v_add_f32_e32 v66, v66, v67
	ds_bpermute_b32 v67, v217, v66
	v_cvt_pk_bf16_f32 v70, v78, v79
	v_cvt_pk_bf16_f32 v71, v80, v81
	global_store_dwordx4 v[82:83], v[74:77], off sc1
	global_store_dwordx4 v[82:83], v[68:71], off offset:256 sc1
	s_and_saveexec_b64 s[16:17], s[0:1]
	s_cbranch_execz .LBB0_1158
	s_waitcnt lgkmcnt(0)
	v_add_f32_e32 v68, v66, v67
	s_lshl_b32 s28, s54, 2
	v_lshlrev_b64 v[66:67], 6, v[176:177]
	s_ashr_i32 s29, s28, 31
	v_lshl_add_u64 v[66:67], s[8:9], 0, v[66:67]
	v_lshl_add_u64 v[66:67], s[28:29], 2, v[66:67]
	s_lshl_b32 s12, s50, 2
	v_lshl_add_u64 v[66:67], v[66:67], 0, s[12:13]
	global_store_dword v[66:67], v68, off
;     __device__ __forceinline__ void operator()(const f32x4 (&acc)[2][2][4][2], const Unit& u, int wr, int wc, int fr, int fq) const {
;     ...
;                 if (mode == EP_RESID) {
; #pragma unroll
;                     for (int m = 0; m < 4; ++m)
; #pragma unroll
;                         for (int bj = 0; bj < 2; ++bj) yall[ai][m][bj] = *(const u32x4*)(xb + (size_t)(row0 + ai * HALF + m * 16) * DM + u.pn * BM + bj * HALF + wc * 32 + 8 * fq);
;                 }
;     ...
;                         const size_t off = (size_t)row * DM + col8;
;                         const u32x4 xi = yall[ai][m][bj];
;                         const f32x4 x0 = (f32x4){bf_lo(xi.x), bf_hi(xi.x), bf_lo(xi.y), bf_hi(xi.y)} + v0, x1 = (f32x4){bf_lo(xi.z), bf_hi(xi.z), bf_lo(xi.w), bf_hi(xi.w)} + v1;
;                         store8(xb + off, x0, x1);
;                         ssacc += (x0[0] * x0[0] + x0[1] * x0[1]) + (x0[2] * x0[2] + x0[3] * x0[3]) + (x1[0] * x1[0] + x1[1] * x1[1]) + (x1[2] * x1[2] + x1[3] * x1[3]);
;                     }
;                 }
;                 if (mode == EP_RESID) {
;                     ssacc += __shfl_xor(ssacc, 16); ssacc += __shfl_xor(ssacc, 32);
;                     if (fq == 0) ss_out[(size_t)row * 16 + u.pn * 4 + wc] = ssacc;
;                 }
.LBB0_1158:
	s_or_b64 exec, exec, s[16:17]
	v_add_u32_e32 v106, 0x80, v174
	v_ashrrev_i32_e32 v107, 31, v106
	v_lshlrev_b64 v[112:113], 11, v[106:107]
	s_waitcnt lgkmcnt(0)
	v_lshl_add_u64 v[66:67], v[172:173], 0, v[112:113]
	global_load_dwordx4 v[108:111], v[66:67], off
	global_load_dwordx4 v[90:93], v[66:67], off offset:256
	v_add_u32_e32 v102, 0x90, v174
	v_ashrrev_i32_e32 v103, 31, v102
	v_add_u32_e32 v96, 0xa0, v174
	v_lshlrev_b64 v[104:105], 11, v[102:103]
	v_ashrrev_i32_e32 v97, 31, v96
	v_add_u32_e32 v94, 0xb0, v174
	v_lshl_add_u64 v[66:67], v[172:173], 0, v[104:105]
	v_lshlrev_b64 v[100:101], 11, v[96:97]
	v_ashrrev_i32_e32 v95, 31, v94
	global_load_dwordx4 v[86:89], v[66:67], off
	global_load_dwordx4 v[82:85], v[66:67], off offset:256
	v_lshl_add_u64 v[66:67], v[172:173], 0, v[100:101]
	v_lshlrev_b64 v[98:99], 11, v[94:95]
	global_load_dwordx4 v[78:81], v[66:67], off
	global_load_dwordx4 v[74:77], v[66:67], off offset:256
	v_lshl_add_u64 v[66:67], v[172:173], 0, v[98:99]
	global_load_dwordx4 v[70:73], v[66:67], off
	s_nop 0
	global_load_dwordx4 v[66:69], v[66:67], off offset:256
	s_waitcnt vmcnt(7)
	v_lshlrev_b32_e32 v114, 16, v108
	v_and_b32_e32 v115, 0xffff0000, v108
	v_lshlrev_b32_e32 v108, 16, v109
	v_and_b32_e32 v109, 0xffff0000, v109
	v_pk_add_f32 v[64:65], v[64:65], v[108:109]
	v_lshlrev_b32_e32 v108, 16, v110
	v_and_b32_e32 v109, 0xffff0000, v110
	v_lshlrev_b32_e32 v110, 16, v111
	v_and_b32_e32 v111, 0xffff0000, v111
	v_pk_add_f32 v[62:63], v[62:63], v[114:115]
	v_pk_add_f32 v[110:111], v[60:61], v[110:111]
	v_pk_add_f32 v[108:109], v[58:59], v[108:109]
	v_lshl_add_u64 v[58:59], s[6:7], 0, v[112:113]
	v_lshl_add_u64 v[112:113], v[170:171], 1, v[58:59]
	v_cvt_pk_bf16_f32 v58, v62, v63
	v_cvt_pk_bf16_f32 v59, v64, v65
	v_cvt_pk_bf16_f32 v60, v108, v109
	v_cvt_pk_bf16_f32 v61, v110, v111
	global_store_dwordx4 v[112:113], v[58:61], off sc1
	s_nop 1
	v_mul_f32_e32 v58, v63, v63
	v_mul_f32_e32 v59, v65, v65
	v_fmac_f32_e32 v58, v62, v62
	v_fmac_f32_e32 v59, v64, v64
	v_add_f32_e32 v58, v58, v59
	v_mul_f32_e32 v59, v109, v109
	v_fmac_f32_e32 v59, v108, v108
	v_add_f32_e32 v58, v59, v58
	v_mul_f32_e32 v59, v111, v111
	v_fmac_f32_e32 v59, v110, v110
	v_add_f32_e32 v62, v59, v58
	s_waitcnt vmcnt(7)
	v_lshlrev_b32_e32 v58, 16, v90
	v_and_b32_e32 v59, 0xffff0000, v90
	v_lshlrev_b32_e32 v60, 16, v91
	v_and_b32_e32 v61, 0xffff0000, v91
	v_pk_add_f32 v[56:57], v[56:57], v[60:61]
	v_pk_add_f32 v[54:55], v[54:55], v[58:59]
	v_lshlrev_b32_e32 v58, 16, v92
	v_and_b32_e32 v59, 0xffff0000, v92
	v_lshlrev_b32_e32 v60, 16, v93
	v_and_b32_e32 v61, 0xffff0000, v93
	v_pk_add_f32 v[60:61], v[52:53], v[60:61]
	v_pk_add_f32 v[58:59], v[50:51], v[58:59]
	v_cvt_pk_bf16_f32 v50, v54, v55
	v_cvt_pk_bf16_f32 v51, v56, v57
	v_cvt_pk_bf16_f32 v52, v58, v59
	v_cvt_pk_bf16_f32 v53, v60, v61
	global_store_dwordx4 v[112:113], v[50:53], off offset:256 sc1
	s_nop 1
	v_mul_f32_e32 v50, v55, v55
	v_mul_f32_e32 v51, v57, v57
	v_fmac_f32_e32 v50, v54, v54
	v_fmac_f32_e32 v51, v56, v56
	v_add_f32_e32 v50, v50, v51
	v_mul_f32_e32 v51, v59, v59
	v_fmac_f32_e32 v51, v58, v58
	v_add_f32_e32 v50, v51, v50
	v_mul_f32_e32 v51, v61, v61
	v_fmac_f32_e32 v51, v60, v60
	v_add_f32_e32 v50, v51, v50
	v_add_f32_e32 v50, v62, v50
	ds_bpermute_b32 v51, v216, v50
	s_waitcnt lgkmcnt(0)
	v_add_f32_e32 v50, v50, v51
	ds_bpermute_b32 v51, v217, v50
	s_and_saveexec_b64 s[16:17], s[0:1]
	s_cbranch_execz .LBB0_1160
	s_waitcnt lgkmcnt(0)
	v_add_f32_e32 v52, v50, v51
	s_lshl_b32 s28, s54, 2
	v_lshlrev_b64 v[50:51], 6, v[106:107]
	s_ashr_i32 s29, s28, 31
	v_lshl_add_u64 v[50:51], s[8:9], 0, v[50:51]
	v_lshl_add_u64 v[50:51], s[28:29], 2, v[50:51]
	s_lshl_b32 s12, s50, 2
	v_lshl_add_u64 v[50:51], v[50:51], 0, s[12:13]
	global_store_dword v[50:51], v52, off
.LBB0_1160:
	s_or_b64 exec, exec, s[16:17]
	s_waitcnt vmcnt(7)
	v_lshlrev_b32_e32 v50, 16, v86
	s_waitcnt lgkmcnt(0)
	v_and_b32_e32 v51, 0xffff0000, v86
	v_lshlrev_b32_e32 v52, 16, v87
	v_and_b32_e32 v53, 0xffff0000, v87
	v_pk_add_f32 v[48:49], v[48:49], v[52:53]
	v_pk_add_f32 v[46:47], v[46:47], v[50:51]
	v_lshlrev_b32_e32 v50, 16, v88
	v_and_b32_e32 v51, 0xffff0000, v88
	v_lshlrev_b32_e32 v52, 16, v89
	v_and_b32_e32 v53, 0xffff0000, v89
	v_pk_add_f32 v[52:53], v[44:45], v[52:53]
	v_pk_add_f32 v[44:45], v[42:43], v[50:51]
	v_lshl_add_u64 v[42:43], s[6:7], 0, v[104:105]
	v_lshl_add_u64 v[50:51], v[170:171], 1, v[42:43]
	v_cvt_pk_bf16_f32 v42, v46, v47
	v_mul_f32_e32 v47, v47, v47
	v_fmac_f32_e32 v47, v46, v46
	v_mul_f32_e32 v46, v49, v49
	v_fmac_f32_e32 v46, v48, v48
	v_add_f32_e32 v46, v47, v46
	v_mul_f32_e32 v47, v45, v45
	v_fmac_f32_e32 v47, v44, v44
	v_add_f32_e32 v46, v47, v46
	v_mul_f32_e32 v47, v53, v53
	v_fmac_f32_e32 v47, v52, v52
	v_cvt_pk_bf16_f32 v43, v48, v49
	v_add_f32_e32 v54, v47, v46
	s_waitcnt vmcnt(6)
	v_lshlrev_b32_e32 v46, 16, v82
	v_and_b32_e32 v47, 0xffff0000, v82
	v_lshlrev_b32_e32 v48, 16, v83
	v_and_b32_e32 v49, 0xffff0000, v83
	v_pk_add_f32 v[40:41], v[40:41], v[48:49]
	v_pk_add_f32 v[38:39], v[38:39], v[46:47]
	v_lshlrev_b32_e32 v46, 16, v84
	v_and_b32_e32 v47, 0xffff0000, v84
	v_pk_add_f32 v[46:47], v[34:35], v[46:47]
	v_mul_f32_e32 v34, v39, v39
	v_mul_f32_e32 v35, v41, v41
	v_fmac_f32_e32 v34, v38, v38
	v_fmac_f32_e32 v35, v40, v40
	v_lshlrev_b32_e32 v48, 16, v85
	v_and_b32_e32 v49, 0xffff0000, v85
	v_add_f32_e32 v34, v34, v35
	v_mul_f32_e32 v35, v47, v47
	v_pk_add_f32 v[48:49], v[36:37], v[48:49]
	v_fmac_f32_e32 v35, v46, v46
	v_add_f32_e32 v34, v35, v34
	v_mul_f32_e32 v35, v49, v49
	v_fmac_f32_e32 v35, v48, v48
	v_add_f32_e32 v34, v35, v34
	v_add_f32_e32 v34, v54, v34
	ds_bpermute_b32 v35, v216, v34
	v_cvt_pk_bf16_f32 v44, v44, v45
	v_cvt_pk_bf16_f32 v45, v52, v53
	v_cvt_pk_bf16_f32 v36, v38, v39
	v_cvt_pk_bf16_f32 v37, v40, v41
	s_waitcnt lgkmcnt(0)
	v_add_f32_e32 v34, v34, v35
	ds_bpermute_b32 v35, v217, v34
	v_cvt_pk_bf16_f32 v38, v46, v47
	v_cvt_pk_bf16_f32 v39, v48, v49
	global_store_dwordx4 v[50:51], v[42:45], off sc1
	global_store_dwordx4 v[50:51], v[36:39], off offset:256 sc1
	s_and_saveexec_b64 s[16:17], s[0:1]
	s_cbranch_execz .LBB0_1162
	s_waitcnt lgkmcnt(0)
	v_add_f32_e32 v36, v34, v35
	s_lshl_b32 s28, s54, 2
	v_lshlrev_b64 v[34:35], 6, v[102:103]
	s_ashr_i32 s29, s28, 31
	v_lshl_add_u64 v[34:35], s[8:9], 0, v[34:35]
	v_lshl_add_u64 v[34:35], s[28:29], 2, v[34:35]
	s_lshl_b32 s12, s50, 2
	v_lshl_add_u64 v[34:35], v[34:35], 0, s[12:13]
	global_store_dword v[34:35], v36, off
;     __device__ __forceinline__ void operator()(const f32x4 (&acc)[2][2][4][2], const Unit& u, int wr, int wc, int fr, int fq) const {
;     ...
;                         const size_t off = (size_t)row * DM + col8;
;                         const u32x4 xi = yall[ai][m][bj];
;                         const f32x4 x0 = (f32x4){bf_lo(xi.x), bf_hi(xi.x), bf_lo(xi.y), bf_hi(xi.y)} + v0, x1 = (f32x4){bf_lo(xi.z), bf_hi(xi.z), bf_lo(xi.w), bf_hi(xi.w)} + v1;
;                         store8(xb + off, x0, x1);
;                         ssacc += (x0[0] * x0[0] + x0[1] * x0[1]) + (x0[2] * x0[2] + x0[3] * x0[3]) + (x1[0] * x1[0] + x1[1] * x1[1]) + (x1[2] * x1[2] + x1[3] * x1[3]);
;                     }
;                 }
;                 if (mode == EP_RESID) {
;                     ssacc += __shfl_xor(ssacc, 16); ssacc += __shfl_xor(ssacc, 32);
;                     if (fq == 0) ss_out[(size_t)row * 16 + u.pn * 4 + wc] = ssacc;
;                 }
.LBB0_1162:
	s_or_b64 exec, exec, s[16:17]
	s_waitcnt vmcnt(7)
	v_lshlrev_b32_e32 v34, 16, v78
	s_waitcnt lgkmcnt(0)
	v_and_b32_e32 v35, 0xffff0000, v78
	v_lshlrev_b32_e32 v36, 16, v79
	v_and_b32_e32 v37, 0xffff0000, v79
	v_pk_add_f32 v[32:33], v[32:33], v[36:37]
	v_pk_add_f32 v[30:31], v[30:31], v[34:35]
	v_lshlrev_b32_e32 v34, 16, v80
	v_and_b32_e32 v35, 0xffff0000, v80
	v_lshlrev_b32_e32 v36, 16, v81
	v_and_b32_e32 v37, 0xffff0000, v81
	v_pk_add_f32 v[36:37], v[28:29], v[36:37]
	v_pk_add_f32 v[28:29], v[26:27], v[34:35]
	v_lshl_add_u64 v[26:27], s[6:7], 0, v[100:101]
	v_lshl_add_u64 v[34:35], v[170:171], 1, v[26:27]
	v_cvt_pk_bf16_f32 v26, v30, v31
	v_mul_f32_e32 v31, v31, v31
	v_fmac_f32_e32 v31, v30, v30
	v_mul_f32_e32 v30, v33, v33
	v_fmac_f32_e32 v30, v32, v32
	v_add_f32_e32 v30, v31, v30
	v_mul_f32_e32 v31, v29, v29
	v_fmac_f32_e32 v31, v28, v28
	v_add_f32_e32 v30, v31, v30
	v_mul_f32_e32 v31, v37, v37
	v_fmac_f32_e32 v31, v36, v36
	v_cvt_pk_bf16_f32 v27, v32, v33
	v_add_f32_e32 v38, v31, v30
	s_waitcnt vmcnt(6)
	v_lshlrev_b32_e32 v30, 16, v74
	v_and_b32_e32 v31, 0xffff0000, v74
	v_lshlrev_b32_e32 v32, 16, v75
	v_and_b32_e32 v33, 0xffff0000, v75
	v_pk_add_f32 v[24:25], v[24:25], v[32:33]
	v_pk_add_f32 v[22:23], v[22:23], v[30:31]
	v_lshlrev_b32_e32 v30, 16, v76
	v_and_b32_e32 v31, 0xffff0000, v76
	v_pk_add_f32 v[30:31], v[18:19], v[30:31]
	v_mul_f32_e32 v18, v23, v23
	v_mul_f32_e32 v19, v25, v25
	v_fmac_f32_e32 v18, v22, v22
	v_fmac_f32_e32 v19, v24, v24
	v_lshlrev_b32_e32 v32, 16, v77
	v_and_b32_e32 v33, 0xffff0000, v77
	v_add_f32_e32 v18, v18, v19
	v_mul_f32_e32 v19, v31, v31
	v_pk_add_f32 v[32:33], v[20:21], v[32:33]
	v_fmac_f32_e32 v19, v30, v30
	v_add_f32_e32 v18, v19, v18
	v_mul_f32_e32 v19, v33, v33
	v_fmac_f32_e32 v19, v32, v32
	v_add_f32_e32 v18, v19, v18
	v_add_f32_e32 v18, v38, v18
	ds_bpermute_b32 v19, v216, v18
	v_cvt_pk_bf16_f32 v28, v28, v29
	v_cvt_pk_bf16_f32 v29, v36, v37
	v_cvt_pk_bf16_f32 v20, v22, v23
	v_cvt_pk_bf16_f32 v21, v24, v25
	s_waitcnt lgkmcnt(0)
	v_add_f32_e32 v18, v18, v19
	ds_bpermute_b32 v19, v217, v18
	v_cvt_pk_bf16_f32 v22, v30, v31
	v_cvt_pk_bf16_f32 v23, v32, v33
	global_store_dwordx4 v[34:35], v[26:29], off sc1
	global_store_dwordx4 v[34:35], v[20:23], off offset:256 sc1
	s_and_saveexec_b64 s[16:17], s[0:1]
	s_cbranch_execz .LBB0_1164
	s_waitcnt lgkmcnt(0)
	v_add_f32_e32 v20, v18, v19
	s_lshl_b32 s28, s54, 2
	v_lshlrev_b64 v[18:19], 6, v[96:97]
	s_ashr_i32 s29, s28, 31
	v_lshl_add_u64 v[18:19], s[8:9], 0, v[18:19]
	v_lshl_add_u64 v[18:19], s[28:29], 2, v[18:19]
	s_lshl_b32 s12, s50, 2
	v_lshl_add_u64 v[18:19], v[18:19], 0, s[12:13]
	global_store_dword v[18:19], v20, off
.LBB0_1164:
	s_or_b64 exec, exec, s[16:17]
	s_waitcnt vmcnt(7)
	v_lshlrev_b32_e32 v18, 16, v70
	s_waitcnt lgkmcnt(0)
	v_and_b32_e32 v19, 0xffff0000, v70
	v_lshlrev_b32_e32 v20, 16, v71
	v_and_b32_e32 v21, 0xffff0000, v71
	v_pk_add_f32 v[16:17], v[16:17], v[20:21]
	v_pk_add_f32 v[14:15], v[14:15], v[18:19]
	v_lshlrev_b32_e32 v18, 16, v72
	v_and_b32_e32 v19, 0xffff0000, v72
	v_lshlrev_b32_e32 v20, 16, v73
	v_and_b32_e32 v21, 0xffff0000, v73
	v_pk_add_f32 v[20:21], v[12:13], v[20:21]
	v_pk_add_f32 v[12:13], v[10:11], v[18:19]
	v_lshl_add_u64 v[10:11], s[6:7], 0, v[98:99]
	v_lshl_add_u64 v[18:19], v[170:171], 1, v[10:11]
	v_cvt_pk_bf16_f32 v10, v14, v15
	v_mul_f32_e32 v15, v15, v15
	v_fmac_f32_e32 v15, v14, v14
	v_mul_f32_e32 v14, v17, v17
	v_fmac_f32_e32 v14, v16, v16
	v_add_f32_e32 v14, v15, v14
	v_mul_f32_e32 v15, v13, v13
	v_fmac_f32_e32 v15, v12, v12
	v_add_f32_e32 v14, v15, v14
	v_mul_f32_e32 v15, v21, v21
	v_fmac_f32_e32 v15, v20, v20
	v_cvt_pk_bf16_f32 v11, v16, v17
	v_add_f32_e32 v22, v15, v14
	s_waitcnt vmcnt(6)
	v_lshlrev_b32_e32 v14, 16, v66
	v_and_b32_e32 v15, 0xffff0000, v66
	v_lshlrev_b32_e32 v16, 16, v67
	v_and_b32_e32 v17, 0xffff0000, v67
	v_pk_add_f32 v[8:9], v[8:9], v[16:17]
	v_pk_add_f32 v[6:7], v[6:7], v[14:15]
	v_lshlrev_b32_e32 v14, 16, v68
	v_and_b32_e32 v15, 0xffff0000, v68
	v_pk_add_f32 v[14:15], v[2:3], v[14:15]
	v_mul_f32_e32 v2, v7, v7
	v_mul_f32_e32 v3, v9, v9
	v_fmac_f32_e32 v2, v6, v6
	v_fmac_f32_e32 v3, v8, v8
	v_lshlrev_b32_e32 v16, 16, v69
	v_and_b32_e32 v17, 0xffff0000, v69
	v_add_f32_e32 v2, v2, v3
	v_mul_f32_e32 v3, v15, v15
	v_pk_add_f32 v[16:17], v[4:5], v[16:17]
	v_fmac_f32_e32 v3, v14, v14
	v_add_f32_e32 v2, v3, v2
	v_mul_f32_e32 v3, v17, v17
	v_fmac_f32_e32 v3, v16, v16
	v_add_f32_e32 v2, v3, v2
	v_add_f32_e32 v2, v22, v2
	ds_bpermute_b32 v3, v216, v2
	v_cvt_pk_bf16_f32 v12, v12, v13
	v_cvt_pk_bf16_f32 v13, v20, v21
	v_cvt_pk_bf16_f32 v4, v6, v7
	v_cvt_pk_bf16_f32 v5, v8, v9
	s_waitcnt lgkmcnt(0)
	v_add_f32_e32 v2, v2, v3
	ds_bpermute_b32 v3, v217, v2
	v_cvt_pk_bf16_f32 v6, v14, v15
	v_cvt_pk_bf16_f32 v7, v16, v17
	global_store_dwordx4 v[18:19], v[10:13], off sc1
	global_store_dwordx4 v[18:19], v[4:7], off offset:256 sc1
	s_and_saveexec_b64 s[16:17], s[0:1]
	s_cbranch_execz .LBB0_1166
	s_waitcnt lgkmcnt(0)
	v_add_f32_e32 v4, v2, v3
	s_lshl_b32 s28, s54, 2
	v_lshlrev_b64 v[2:3], 6, v[94:95]
	s_ashr_i32 s29, s28, 31
	v_lshl_add_u64 v[2:3], s[8:9], 0, v[2:3]
	v_lshl_add_u64 v[2:3], s[28:29], 2, v[2:3]
	s_lshl_b32 s12, s50, 2
	v_lshl_add_u64 v[2:3], v[2:3], 0, s[12:13]
	global_store_dword v[2:3], v4, off

;     __device__ __forceinline__ void operator()(const f32x4 (&acc)[2][2][4][2], const Unit& u, int wr, int wc, int fr, int fq) const {
;     ...
;             for (int ai = 0; ai < 2; ++ai)
; #pragma unroll
;                 for (int m = 0; m < 4; ++m) {
;                     part[ai][m] = (f32x4){0.f, 0.f, 0.f, 0.f};
;                     if (4 * fq < rs_n) part[ai][m] = *(const f32x4*)(rs + (size_t)(row0 + ai * HALF + m * 16) * rs_ld + rs_off + 4 * fq);
;                 }
; #pragma unroll
;             for (int ai = 0; ai < 2; ++ai)
; #pragma unroll
;                 for (int m = 0; m < 4; ++m) {
;                     float t = (part[ai][m][0] + part[ai][m][1]) + (part[ai][m][2] + part[ai][m][3]);
;                     t += __shfl_xor(t, 16); t += __shfl_xor(t, 32);
;                     rsc[ai][m] = __builtin_amdgcn_rsqf(t * rs_inv + EPS);
;                 }
.LBB0_1234:
	v_lshl_add_u32 v174, s49, 8, v167
	v_ashrrev_i32_e32 v175, 31, v174
	v_lshlrev_b64 v[130:131], 6, v[174:175]
	v_lshl_add_u64 v[130:131], v[148:149], 0, v[130:131]
	global_load_dwordx4 v[178:181], v[130:131], off
	v_or_b32_e32 v168, 16, v174
	v_ashrrev_i32_e32 v169, 31, v168
	v_lshlrev_b64 v[130:131], 6, v[168:169]
	v_lshl_add_u64 v[130:131], v[148:149], 0, v[130:131]
	global_load_dwordx4 v[182:185], v[130:131], off
	v_or_b32_e32 v164, 32, v174
	v_ashrrev_i32_e32 v165, 31, v164
	v_lshlrev_b64 v[130:131], 6, v[164:165]
	v_lshl_add_u64 v[130:131], v[148:149], 0, v[130:131]
	global_load_dwordx4 v[186:189], v[130:131], off
	v_or_b32_e32 v162, 48, v174
	v_ashrrev_i32_e32 v163, 31, v162
	v_lshlrev_b64 v[130:131], 6, v[162:163]
	v_lshl_add_u64 v[130:131], v[148:149], 0, v[130:131]
	global_load_dwordx4 v[190:193], v[130:131], off
	v_add_u32_e32 v160, 0x80, v174
	v_ashrrev_i32_e32 v161, 31, v160
	v_lshlrev_b64 v[130:131], 6, v[160:161]
	v_lshl_add_u64 v[130:131], v[148:149], 0, v[130:131]
	global_load_dwordx4 v[196:199], v[130:131], off
	v_add_u32_e32 v158, 0x90, v174
	v_ashrrev_i32_e32 v159, 31, v158
	v_lshlrev_b64 v[130:131], 6, v[158:159]
	v_add_u32_e32 v156, 0xa0, v174
	v_lshl_add_u64 v[130:131], v[148:149], 0, v[130:131]
	v_ashrrev_i32_e32 v157, 31, v156
	global_load_dwordx4 v[138:141], v[130:131], off
	v_lshlrev_b64 v[130:131], 6, v[156:157]
	v_add_u32_e32 v154, 0xb0, v174
	v_lshl_add_u64 v[130:131], v[148:149], 0, v[130:131]
	v_ashrrev_i32_e32 v155, 31, v154
	global_load_dwordx4 v[134:137], v[130:131], off
	v_lshlrev_b64 v[130:131], 6, v[154:155]
	v_lshl_add_u64 v[130:131], v[148:149], 0, v[130:131]
	global_load_dwordx4 v[130:133], v[130:131], off
	s_mov_b64 s[16:17], -1
	s_andn2_b64 vcc, exec, s[0:1]
	s_waitcnt vmcnt(0)
	v_mov_b32_e32 v200, v179
	v_mov_b32_e32 v201, v180
	v_mov_b32_e32 v179, v181
	v_pk_add_f32 v[178:179], v[200:201], v[178:179]
	v_mov_b32_e32 v180, v183
	v_add_f32_e32 v166, v178, v179
	ds_bpermute_b32 v170, v216, v166
	v_mov_b32_e32 v181, v184
	v_mov_b32_e32 v183, v185
	v_pk_add_f32 v[180:181], v[180:181], v[182:183]
	s_waitcnt lgkmcnt(0)
	v_add_f32_e32 v166, v166, v170
	ds_bpermute_b32 v170, v217, v166
	s_waitcnt lgkmcnt(0)
	v_add_f32_e32 v166, v166, v170
	v_fmamk_f32 v166, v166, 0x3a800000, v195
	v_rsq_f32_e32 v178, v166
	v_add_f32_e32 v166, v180, v181
	ds_bpermute_b32 v170, v216, v166
	v_mov_b32_e32 v180, v187
	v_mov_b32_e32 v181, v188
	v_mov_b32_e32 v187, v189
	v_pk_add_f32 v[180:181], v[180:181], v[186:187]
	s_waitcnt lgkmcnt(0)
	v_add_f32_e32 v166, v166, v170
	ds_bpermute_b32 v170, v217, v166
	s_waitcnt lgkmcnt(0)
	v_add_f32_e32 v166, v166, v170
	v_fmamk_f32 v166, v166, 0x3a800000, v195
	v_rsq_f32_e32 v176, v166
	v_add_f32_e32 v166, v180, v181
	ds_bpermute_b32 v170, v216, v166
	v_mov_b32_e32 v180, v191
	v_mov_b32_e32 v181, v192
	v_mov_b32_e32 v191, v193
	v_pk_add_f32 v[180:181], v[180:181], v[190:191]
	s_waitcnt lgkmcnt(0)
	v_add_f32_e32 v166, v166, v170
	ds_bpermute_b32 v170, v217, v166
	v_pk_mul_f32 v[106:107], v[106:107], v[176:177] op_sel_hi:[1,0]
	v_pk_mul_f32 v[112:113], v[112:113], v[176:177] op_sel_hi:[1,0]
	v_max_f32_e32 v106, 0, v106
	v_max_f32_e32 v107, 0, v107
	s_waitcnt lgkmcnt(0)
	v_add_f32_e32 v166, v166, v170
	v_fmamk_f32 v166, v166, 0x3a800000, v195
	v_rsq_f32_e32 v172, v166
	v_add_f32_e32 v166, v180, v181
	ds_bpermute_b32 v170, v216, v166
	v_mov_b32_e32 v180, v197
	v_mov_b32_e32 v181, v198
	v_mov_b32_e32 v197, v199
	v_pk_add_f32 v[180:181], v[180:181], v[196:197]
	s_waitcnt lgkmcnt(0)
	v_add_f32_e32 v166, v166, v170
	ds_bpermute_b32 v170, v217, v166
	v_pk_mul_f32 v[110:111], v[110:111], v[176:177] op_sel_hi:[1,0]
	v_pk_mul_f32 v[108:109], v[108:109], v[176:177] op_sel_hi:[1,0]
	v_max_f32_e32 v110, 0, v110
	v_max_f32_e32 v111, 0, v111
	s_waitcnt lgkmcnt(0)
	v_add_f32_e32 v166, v166, v170
	v_fmamk_f32 v166, v166, 0x3a800000, v195
	v_rsq_f32_e32 v170, v166
	v_add_f32_e32 v166, v180, v181
	ds_bpermute_b32 v179, v216, v166
	v_mov_b32_e32 v180, v139
	v_mov_b32_e32 v181, v140
	v_mov_b32_e32 v139, v141
	v_mov_b32_e32 v140, v135
	s_waitcnt lgkmcnt(0)
	v_add_f32_e32 v166, v166, v179
	ds_bpermute_b32 v179, v217, v166
	v_mov_b32_e32 v141, v136
	v_mov_b32_e32 v135, v137
	v_mov_b32_e32 v136, v131
	v_mov_b32_e32 v137, v132
	s_waitcnt lgkmcnt(0)
;     __device__ __forceinline__ void operator()(const f32x4 (&acc)[2][2][4][2], const Unit& u, int wr, int wc, int fr, int fq) const {
;     ...
;                     float t = (part[ai][m][0] + part[ai][m][1]) + (part[ai][m][2] + part[ai][m][3]);
;                     t += __shfl_xor(t, 16); t += __shfl_xor(t, 32);
;                     rsc[ai][m] = __builtin_amdgcn_rsqf(t * rs_inv + EPS);
;     ...
;                     f32x4 v0 = acc[ai][bj][m][0] * rs1, v1 = acc[ai][bj][m][1] * rs1;
;                     if (mode == EP_PLAIN) { store8(O + (size_t)row * ldc + col8, v0, v1); }
;                     else if (mode == EP_RELU2) {
; #pragma unroll
;                         for (int e = 0; e < 4; ++e) { float a = fmaxf(v0[e], 0.f), b = fmaxf(v1[e], 0.f); v0[e] = a * a; v1[e] = b * b; }
;                         store8(O + (size_t)row * ldc + col8, v0, v1);
	v_pk_mul_f32 v[122:123], v[122:123], v[178:179] op_sel_hi:[1,0]
	v_mov_b32_e32 v131, v133
	v_pk_mul_f32 v[128:129], v[128:129], v[178:179] op_sel_hi:[1,0]
	v_max_f32_e32 v122, 0, v122
	v_max_f32_e32 v123, 0, v123
	v_pk_add_f32 v[130:131], v[136:137], v[130:131]
	v_lshl_or_b32 v132, s48, 8, v173
	v_pk_mul_f32 v[126:127], v[126:127], v[178:179] op_sel_hi:[1,0]
	v_pk_mul_f32 v[124:125], v[124:125], v[178:179] op_sel_hi:[1,0]
	v_pk_mul_f32 v[136:137], v[122:123], v[122:123]
	v_max_f32_e32 v122, 0, v128
	v_max_f32_e32 v123, 0, v129
	v_max_f32_e32 v126, 0, v126
	v_max_f32_e32 v127, 0, v127
	v_max_f32_e32 v124, 0, v124
	v_max_f32_e32 v125, 0, v125
	v_pk_mul_f32 v[128:129], v[122:123], v[122:123]
	v_lshlrev_b64 v[122:123], 13, v[174:175]
	v_ashrrev_i32_e32 v133, 31, v132
	v_pk_add_f32 v[134:135], v[140:141], v[134:135]
	v_pk_mul_f32 v[126:127], v[126:127], v[126:127]
	v_pk_mul_f32 v[140:141], v[124:125], v[124:125]
	v_lshl_add_u64 v[124:125], s[6:7], 0, v[122:123]
	v_lshlrev_b64 v[122:123], 1, v[132:133]
	v_pk_mul_f32 v[114:115], v[114:115], v[178:179] op_sel_hi:[1,0]
	v_lshl_add_u64 v[132:133], v[124:125], 0, v[122:123]
	v_cvt_pk_bf16_f32 v124, v126, v127
	v_cvt_pk_bf16_f32 v125, v128, v129
	v_cvt_pk_bf16_f32 v126, v136, v137
	v_cvt_pk_bf16_f32 v127, v140, v141
	v_pk_mul_f32 v[120:121], v[120:121], v[178:179] op_sel_hi:[1,0]
	v_pk_mul_f32 v[118:119], v[118:119], v[178:179] op_sel_hi:[1,0]
	v_pk_mul_f32 v[116:117], v[116:117], v[178:179] op_sel_hi:[1,0]
	v_max_f32_e32 v114, 0, v114
	v_max_f32_e32 v115, 0, v115
	global_store_dwordx4 v[132:133], v[124:127], off sc1
	v_max_f32_e32 v118, 0, v118
	v_max_f32_e32 v119, 0, v119
	v_pk_mul_f32 v[124:125], v[114:115], v[114:115]
	v_max_f32_e32 v114, 0, v120
	v_max_f32_e32 v116, 0, v116
	v_max_f32_e32 v115, 0, v121
	v_max_f32_e32 v117, 0, v117
	v_pk_mul_f32 v[118:119], v[118:119], v[118:119]
	v_pk_mul_f32 v[120:121], v[114:115], v[114:115]
	v_pk_mul_f32 v[126:127], v[116:117], v[116:117]
	v_cvt_pk_bf16_f32 v114, v118, v119
	v_cvt_pk_bf16_f32 v115, v120, v121
	v_cvt_pk_bf16_f32 v116, v124, v125
	v_cvt_pk_bf16_f32 v117, v126, v127
	global_store_dwordx4 v[132:133], v[114:117], off offset:256 sc1
	v_max_f32_e32 v108, 0, v108
	v_max_f32_e32 v109, 0, v109
	v_pk_mul_f32 v[114:115], v[106:107], v[106:107]
	v_max_f32_e32 v106, 0, v112
	v_max_f32_e32 v107, 0, v113
	v_pk_mul_f32 v[112:113], v[106:107], v[106:107]
	v_lshlrev_b64 v[106:107], 13, v[168:169]
	v_pk_mul_f32 v[110:111], v[110:111], v[110:111]
	v_pk_mul_f32 v[116:117], v[108:109], v[108:109]
	v_lshl_add_u64 v[106:107], s[6:7], 0, v[106:107]
	v_pk_mul_f32 v[98:99], v[98:99], v[176:177] op_sel_hi:[1,0]
	v_lshl_add_u64 v[118:119], v[106:107], 0, v[122:123]
	v_cvt_pk_bf16_f32 v106, v110, v111
	v_cvt_pk_bf16_f32 v107, v112, v113
	v_cvt_pk_bf16_f32 v108, v114, v115
	v_cvt_pk_bf16_f32 v109, v116, v117
	v_pk_mul_f32 v[104:105], v[104:105], v[176:177] op_sel_hi:[1,0]
	v_pk_mul_f32 v[102:103], v[102:103], v[176:177] op_sel_hi:[1,0]
	v_pk_mul_f32 v[100:101], v[100:101], v[176:177] op_sel_hi:[1,0]
	v_max_f32_e32 v98, 0, v98
	v_max_f32_e32 v99, 0, v99
	global_store_dwordx4 v[118:119], v[106:109], off sc1
	v_max_f32_e32 v102, 0, v102
	v_max_f32_e32 v103, 0, v103
	v_pk_mul_f32 v[106:107], v[98:99], v[98:99]
	v_max_f32_e32 v98, 0, v104
	v_max_f32_e32 v100, 0, v100
	v_max_f32_e32 v99, 0, v105
	v_max_f32_e32 v101, 0, v101
	v_pk_mul_f32 v[102:103], v[102:103], v[102:103]
	v_pk_mul_f32 v[104:105], v[98:99], v[98:99]
	v_pk_mul_f32 v[108:109], v[100:101], v[100:101]
	v_pk_mul_f32 v[90:91], v[90:91], v[172:173] op_sel_hi:[1,0]
	v_pk_add_f32 v[138:139], v[180:181], v[138:139]
	v_cvt_pk_bf16_f32 v98, v102, v103
	v_cvt_pk_bf16_f32 v99, v104, v105
	v_cvt_pk_bf16_f32 v100, v106, v107
	v_cvt_pk_bf16_f32 v101, v108, v109
	v_pk_mul_f32 v[96:97], v[96:97], v[172:173] op_sel_hi:[1,0]
	v_pk_mul_f32 v[94:95], v[94:95], v[172:173] op_sel_hi:[1,0]
	v_pk_mul_f32 v[92:93], v[92:93], v[172:173] op_sel_hi:[1,0]
	v_max_f32_e32 v90, 0, v90
	v_max_f32_e32 v91, 0, v91
	v_add_f32_e32 v138, v138, v139
	global_store_dwordx4 v[118:119], v[98:101], off offset:256 sc1
	v_max_f32_e32 v94, 0, v94
	v_max_f32_e32 v95, 0, v95
	v_lshlrev_b64 v[98:99], 13, v[164:165]
	v_pk_mul_f32 v[100:101], v[90:91], v[90:91]
	v_max_f32_e32 v90, 0, v96
	v_max_f32_e32 v92, 0, v92
	v_max_f32_e32 v91, 0, v97
	v_max_f32_e32 v93, 0, v93
	ds_bpermute_b32 v139, v216, v138
	v_pk_mul_f32 v[94:95], v[94:95], v[94:95]
	v_pk_mul_f32 v[96:97], v[90:91], v[90:91]
	v_pk_mul_f32 v[102:103], v[92:93], v[92:93]
	v_lshl_add_u64 v[90:91], s[6:7], 0, v[98:99]
	v_pk_mul_f32 v[82:83], v[82:83], v[172:173] op_sel_hi:[1,0]
	v_lshl_add_u64 v[98:99], v[90:91], 0, v[122:123]
	v_cvt_pk_bf16_f32 v90, v94, v95
	v_cvt_pk_bf16_f32 v91, v96, v97
	v_cvt_pk_bf16_f32 v92, v100, v101
	v_cvt_pk_bf16_f32 v93, v102, v103
	v_pk_mul_f32 v[88:89], v[88:89], v[172:173] op_sel_hi:[1,0]
	v_pk_mul_f32 v[86:87], v[86:87], v[172:173] op_sel_hi:[1,0]
	v_pk_mul_f32 v[84:85], v[84:85], v[172:173] op_sel_hi:[1,0]
	v_max_f32_e32 v82, 0, v82
	v_max_f32_e32 v83, 0, v83
	global_store_dwordx4 v[98:99], v[90:93], off sc1
	v_max_f32_e32 v86, 0, v86
	v_max_f32_e32 v87, 0, v87
	v_pk_mul_f32 v[90:91], v[82:83], v[82:83]
	v_max_f32_e32 v82, 0, v88
	v_max_f32_e32 v84, 0, v84
	v_max_f32_e32 v83, 0, v89
	v_max_f32_e32 v85, 0, v85
	v_pk_mul_f32 v[86:87], v[86:87], v[86:87]
	v_pk_mul_f32 v[88:89], v[82:83], v[82:83]
	v_pk_mul_f32 v[92:93], v[84:85], v[84:85]
	v_pk_mul_f32 v[74:75], v[74:75], v[170:171] op_sel_hi:[1,0]
	v_add_f32_e32 v166, v166, v179
	v_cvt_pk_bf16_f32 v82, v86, v87
	v_cvt_pk_bf16_f32 v83, v88, v89
	v_cvt_pk_bf16_f32 v84, v90, v91
	v_cvt_pk_bf16_f32 v85, v92, v93
	v_pk_mul_f32 v[80:81], v[80:81], v[170:171] op_sel_hi:[1,0]
	v_max_f32_e32 v74, 0, v74
	v_max_f32_e32 v75, 0, v75
	v_fmamk_f32 v166, v166, 0x3a800000, v195
	s_waitcnt lgkmcnt(0)
;     __device__ __forceinline__ void operator()(const f32x4 (&acc)[2][2][4][2], const Unit& u, int wr, int wc, int fr, int fq) const {
;     ...
;                     float t = (part[ai][m][0] + part[ai][m][1]) + (part[ai][m][2] + part[ai][m][3]);
;                     t += __shfl_xor(t, 16); t += __shfl_xor(t, 32);
;                     rsc[ai][m] = __builtin_amdgcn_rsqf(t * rs_inv + EPS);
;     ...
;                     f32x4 v0 = acc[ai][bj][m][0] * rs1, v1 = acc[ai][bj][m][1] * rs1;
;                     if (mode == EP_PLAIN) { store8(O + (size_t)row * ldc + col8, v0, v1); }
;                     else if (mode == EP_RELU2) {
; #pragma unroll
;                         for (int e = 0; e < 4; ++e) { float a = fmaxf(v0[e], 0.f), b = fmaxf(v1[e], 0.f); v0[e] = a * a; v1[e] = b * b; }
;                         store8(O + (size_t)row * ldc + col8, v0, v1);
	v_add_f32_e32 v138, v138, v139
	global_store_dwordx4 v[98:99], v[82:85], off offset:256 sc1
	v_pk_mul_f32 v[78:79], v[78:79], v[170:171] op_sel_hi:[1,0]
	v_pk_mul_f32 v[76:77], v[76:77], v[170:171] op_sel_hi:[1,0]
	v_pk_mul_f32 v[82:83], v[74:75], v[74:75]
	v_max_f32_e32 v74, 0, v80
	v_max_f32_e32 v75, 0, v81
	v_rsq_f32_e32 v166, v166
	ds_bpermute_b32 v139, v217, v138
	v_add_f32_e32 v134, v134, v135
	v_max_f32_e32 v78, 0, v78
	v_max_f32_e32 v79, 0, v79
	v_max_f32_e32 v76, 0, v76
	v_max_f32_e32 v77, 0, v77
	v_pk_mul_f32 v[80:81], v[74:75], v[74:75]
	v_lshlrev_b64 v[74:75], 13, v[162:163]
	ds_bpermute_b32 v135, v216, v134
	v_pk_mul_f32 v[78:79], v[78:79], v[78:79]
	v_pk_mul_f32 v[84:85], v[76:77], v[76:77]
	v_lshl_add_u64 v[74:75], s[6:7], 0, v[74:75]
	v_pk_mul_f32 v[66:67], v[66:67], v[170:171] op_sel_hi:[1,0]
	v_lshl_add_u64 v[86:87], v[74:75], 0, v[122:123]
	v_cvt_pk_bf16_f32 v74, v78, v79
	v_cvt_pk_bf16_f32 v75, v80, v81
	v_cvt_pk_bf16_f32 v76, v82, v83
	v_cvt_pk_bf16_f32 v77, v84, v85
	v_pk_mul_f32 v[72:73], v[72:73], v[170:171] op_sel_hi:[1,0]
	v_pk_mul_f32 v[70:71], v[70:71], v[170:171] op_sel_hi:[1,0]
	v_pk_mul_f32 v[68:69], v[68:69], v[170:171] op_sel_hi:[1,0]
	v_max_f32_e32 v66, 0, v66
	v_max_f32_e32 v67, 0, v67
	global_store_dwordx4 v[86:87], v[74:77], off sc1
	v_max_f32_e32 v70, 0, v70
	v_max_f32_e32 v71, 0, v71
	v_pk_mul_f32 v[74:75], v[66:67], v[66:67]
	v_max_f32_e32 v66, 0, v72
	v_max_f32_e32 v68, 0, v68
	v_max_f32_e32 v67, 0, v73
	v_max_f32_e32 v69, 0, v69
	v_pk_mul_f32 v[70:71], v[70:71], v[70:71]
	v_pk_mul_f32 v[72:73], v[66:67], v[66:67]
	v_pk_mul_f32 v[76:77], v[68:69], v[68:69]
	v_pk_mul_f32 v[58:59], v[58:59], v[166:167] op_sel_hi:[1,0]
	s_waitcnt lgkmcnt(1)
	v_add_f32_e32 v138, v138, v139
	v_cvt_pk_bf16_f32 v66, v70, v71
	v_cvt_pk_bf16_f32 v67, v72, v73
	v_cvt_pk_bf16_f32 v68, v74, v75
	v_cvt_pk_bf16_f32 v69, v76, v77
	v_pk_mul_f32 v[64:65], v[64:65], v[166:167] op_sel_hi:[1,0]
	v_max_f32_e32 v58, 0, v58
	v_max_f32_e32 v59, 0, v59
	v_fmamk_f32 v138, v138, 0x3a800000, v195
	s_waitcnt lgkmcnt(0)
	v_add_f32_e32 v134, v134, v135
	v_add_f32_e32 v130, v130, v131
	global_store_dwordx4 v[86:87], v[66:69], off offset:256 sc1
	v_pk_mul_f32 v[62:63], v[62:63], v[166:167] op_sel_hi:[1,0]
	v_pk_mul_f32 v[60:61], v[60:61], v[166:167] op_sel_hi:[1,0]
	v_pk_mul_f32 v[66:67], v[58:59], v[58:59]
	v_max_f32_e32 v58, 0, v64
	v_max_f32_e32 v59, 0, v65
	v_rsq_f32_e32 v138, v138
	ds_bpermute_b32 v135, v217, v134
	ds_bpermute_b32 v131, v216, v130
	v_max_f32_e32 v62, 0, v62
	v_max_f32_e32 v63, 0, v63
	v_max_f32_e32 v60, 0, v60
	v_max_f32_e32 v61, 0, v61
	v_pk_mul_f32 v[64:65], v[58:59], v[58:59]
	v_lshlrev_b64 v[58:59], 13, v[160:161]
	v_pk_mul_f32 v[62:63], v[62:63], v[62:63]
	v_pk_mul_f32 v[68:69], v[60:61], v[60:61]
	v_lshl_add_u64 v[58:59], s[6:7], 0, v[58:59]
	v_pk_mul_f32 v[50:51], v[50:51], v[166:167] op_sel_hi:[1,0]
	v_lshl_add_u64 v[70:71], v[58:59], 0, v[122:123]
	v_cvt_pk_bf16_f32 v58, v62, v63
	v_cvt_pk_bf16_f32 v59, v64, v65
	v_cvt_pk_bf16_f32 v60, v66, v67
	v_cvt_pk_bf16_f32 v61, v68, v69
	v_pk_mul_f32 v[56:57], v[56:57], v[166:167] op_sel_hi:[1,0]
	v_pk_mul_f32 v[54:55], v[54:55], v[166:167] op_sel_hi:[1,0]
	v_pk_mul_f32 v[52:53], v[52:53], v[166:167] op_sel_hi:[1,0]
	v_max_f32_e32 v50, 0, v50
	v_max_f32_e32 v51, 0, v51
	global_store_dwordx4 v[70:71], v[58:61], off sc1
	v_max_f32_e32 v54, 0, v54
	v_max_f32_e32 v55, 0, v55
	v_pk_mul_f32 v[58:59], v[50:51], v[50:51]
	v_max_f32_e32 v50, 0, v56
	v_max_f32_e32 v52, 0, v52
	v_max_f32_e32 v51, 0, v57
	v_max_f32_e32 v53, 0, v53
	v_pk_mul_f32 v[54:55], v[54:55], v[54:55]
	v_pk_mul_f32 v[56:57], v[50:51], v[50:51]
	v_pk_mul_f32 v[60:61], v[52:53], v[52:53]
	v_pk_mul_f32 v[42:43], v[42:43], v[138:139] op_sel_hi:[1,0]
	s_waitcnt lgkmcnt(1)
	v_add_f32_e32 v134, v134, v135
	s_waitcnt lgkmcnt(0)
	v_add_f32_e32 v130, v130, v131
	v_cvt_pk_bf16_f32 v50, v54, v55
	v_cvt_pk_bf16_f32 v51, v56, v57
	v_cvt_pk_bf16_f32 v52, v58, v59
	v_cvt_pk_bf16_f32 v53, v60, v61
	v_pk_mul_f32 v[48:49], v[48:49], v[138:139] op_sel_hi:[1,0]
	v_max_f32_e32 v42, 0, v42
	v_max_f32_e32 v43, 0, v43
	v_fmamk_f32 v134, v134, 0x3a800000, v195
	ds_bpermute_b32 v131, v217, v130
	global_store_dwordx4 v[70:71], v[50:53], off offset:256 sc1
	v_pk_mul_f32 v[46:47], v[46:47], v[138:139] op_sel_hi:[1,0]
	v_pk_mul_f32 v[44:45], v[44:45], v[138:139] op_sel_hi:[1,0]
	v_pk_mul_f32 v[50:51], v[42:43], v[42:43]
	v_max_f32_e32 v42, 0, v48
	v_max_f32_e32 v43, 0, v49
	v_rsq_f32_e32 v134, v134
	v_max_f32_e32 v46, 0, v46
	v_max_f32_e32 v47, 0, v47
	v_max_f32_e32 v44, 0, v44
	v_max_f32_e32 v45, 0, v45
	v_pk_mul_f32 v[48:49], v[42:43], v[42:43]
	v_lshlrev_b64 v[42:43], 13, v[158:159]
	v_pk_mul_f32 v[46:47], v[46:47], v[46:47]
	v_pk_mul_f32 v[52:53], v[44:45], v[44:45]
	v_lshl_add_u64 v[42:43], s[6:7], 0, v[42:43]
	v_pk_mul_f32 v[34:35], v[34:35], v[138:139] op_sel_hi:[1,0]
	v_lshl_add_u64 v[54:55], v[42:43], 0, v[122:123]
	v_cvt_pk_bf16_f32 v42, v46, v47
	v_cvt_pk_bf16_f32 v43, v48, v49
	v_cvt_pk_bf16_f32 v44, v50, v51
	v_cvt_pk_bf16_f32 v45, v52, v53
	v_pk_mul_f32 v[40:41], v[40:41], v[138:139] op_sel_hi:[1,0]
	v_pk_mul_f32 v[38:39], v[38:39], v[138:139] op_sel_hi:[1,0]
	v_pk_mul_f32 v[36:37], v[36:37], v[138:139] op_sel_hi:[1,0]
	v_max_f32_e32 v34, 0, v34
	v_max_f32_e32 v35, 0, v35
	global_store_dwordx4 v[54:55], v[42:45], off sc1
	v_max_f32_e32 v38, 0, v38
	v_max_f32_e32 v39, 0, v39
	v_pk_mul_f32 v[42:43], v[34:35], v[34:35]
	v_max_f32_e32 v34, 0, v40
	v_max_f32_e32 v36, 0, v36
	v_max_f32_e32 v35, 0, v41
	v_max_f32_e32 v37, 0, v37
	s_waitcnt lgkmcnt(0)
; __device__ __forceinline__ unsigned pk_bf16(float lo, float hi) { typedef float f2_t __attribute__((ext_vector_type(2))); typedef __bf16 b2_t __attribute__((ext_vector_type(2))); f2_t v = {lo, hi}; b2_t b = __builtin_convertvector(v, b2_t); return __builtin_bit_cast(unsigned, b); }
;     __device__ __forceinline__ void store8(bf16_t* p, f32x4 v0, f32x4 v1) const {
;         u32x4 w; w.x = pk_bf16(v0[0], v0[1]); w.y = pk_bf16(v0[2], v0[3]); w.z = pk_bf16(v1[0], v1[1]); w.w = pk_bf16(v1[2], v1[3]); *(u32x4*)p = w; }
;     __device__ __forceinline__ void operator()(const f32x4 (&acc)[2][2][4][2], const Unit& u, int wr, int wc, int fr, int fq) const {
;     ...
;                     f32x4 v0 = acc[ai][bj][m][0] * rs1, v1 = acc[ai][bj][m][1] * rs1;
;                     if (mode == EP_PLAIN) { store8(O + (size_t)row * ldc + col8, v0, v1); }
;                     else if (mode == EP_RELU2) {
; #pragma unroll
;                         for (int e = 0; e < 4; ++e) { float a = fmaxf(v0[e], 0.f), b = fmaxf(v1[e], 0.f); v0[e] = a * a; v1[e] = b * b; }
;                         store8(O + (size_t)row * ldc + col8, v0, v1);
	v_add_f32_e32 v130, v130, v131
	v_pk_mul_f32 v[38:39], v[38:39], v[38:39]
	v_pk_mul_f32 v[40:41], v[34:35], v[34:35]
	v_pk_mul_f32 v[44:45], v[36:37], v[36:37]
	v_pk_mul_f32 v[26:27], v[26:27], v[134:135] op_sel_hi:[1,0]
	v_fmamk_f32 v130, v130, 0x3a800000, v195
	v_cvt_pk_bf16_f32 v34, v38, v39
	v_cvt_pk_bf16_f32 v35, v40, v41
	v_cvt_pk_bf16_f32 v36, v42, v43
	v_cvt_pk_bf16_f32 v37, v44, v45
	v_pk_mul_f32 v[32:33], v[32:33], v[134:135] op_sel_hi:[1,0]
	v_pk_mul_f32 v[30:31], v[30:31], v[134:135] op_sel_hi:[1,0]
	v_pk_mul_f32 v[28:29], v[28:29], v[134:135] op_sel_hi:[1,0]
	v_max_f32_e32 v26, 0, v26
	v_max_f32_e32 v27, 0, v27
	v_rsq_f32_e32 v130, v130
	global_store_dwordx4 v[54:55], v[34:37], off offset:256 sc1
	v_max_f32_e32 v30, 0, v30
	v_max_f32_e32 v31, 0, v31
	v_lshlrev_b64 v[34:35], 13, v[156:157]
	v_pk_mul_f32 v[36:37], v[26:27], v[26:27]
	v_max_f32_e32 v26, 0, v32
	v_max_f32_e32 v28, 0, v28
	v_max_f32_e32 v27, 0, v33
	v_max_f32_e32 v29, 0, v29
	v_pk_mul_f32 v[30:31], v[30:31], v[30:31]
	v_pk_mul_f32 v[32:33], v[26:27], v[26:27]
	v_pk_mul_f32 v[38:39], v[28:29], v[28:29]
	v_lshl_add_u64 v[26:27], s[6:7], 0, v[34:35]
	v_pk_mul_f32 v[18:19], v[18:19], v[134:135] op_sel_hi:[1,0]
	v_lshl_add_u64 v[34:35], v[26:27], 0, v[122:123]
	v_cvt_pk_bf16_f32 v26, v30, v31
	v_cvt_pk_bf16_f32 v27, v32, v33
	v_cvt_pk_bf16_f32 v28, v36, v37
	v_cvt_pk_bf16_f32 v29, v38, v39
	v_pk_mul_f32 v[24:25], v[24:25], v[134:135] op_sel_hi:[1,0]
	v_pk_mul_f32 v[22:23], v[22:23], v[134:135] op_sel_hi:[1,0]
	v_pk_mul_f32 v[20:21], v[20:21], v[134:135] op_sel_hi:[1,0]
	v_max_f32_e32 v18, 0, v18
	v_max_f32_e32 v19, 0, v19
	global_store_dwordx4 v[34:35], v[26:29], off sc1
	v_max_f32_e32 v22, 0, v22
	v_max_f32_e32 v23, 0, v23
	v_pk_mul_f32 v[26:27], v[18:19], v[18:19]
	v_max_f32_e32 v18, 0, v24
	v_max_f32_e32 v20, 0, v20
	v_max_f32_e32 v19, 0, v25
	v_max_f32_e32 v21, 0, v21
	v_pk_mul_f32 v[22:23], v[22:23], v[22:23]
	v_pk_mul_f32 v[24:25], v[18:19], v[18:19]
	v_pk_mul_f32 v[28:29], v[20:21], v[20:21]
	v_pk_mul_f32 v[10:11], v[10:11], v[130:131] op_sel_hi:[1,0]
	v_cvt_pk_bf16_f32 v18, v22, v23
	v_cvt_pk_bf16_f32 v19, v24, v25
	v_cvt_pk_bf16_f32 v20, v26, v27
	v_cvt_pk_bf16_f32 v21, v28, v29
	v_pk_mul_f32 v[16:17], v[16:17], v[130:131] op_sel_hi:[1,0]
	v_max_f32_e32 v10, 0, v10
	v_max_f32_e32 v11, 0, v11
	global_store_dwordx4 v[34:35], v[18:21], off offset:256 sc1
	v_pk_mul_f32 v[14:15], v[14:15], v[130:131] op_sel_hi:[1,0]
	v_pk_mul_f32 v[12:13], v[12:13], v[130:131] op_sel_hi:[1,0]
	v_pk_mul_f32 v[18:19], v[10:11], v[10:11]
	v_max_f32_e32 v10, 0, v16
	v_max_f32_e32 v11, 0, v17
	v_max_f32_e32 v14, 0, v14
	v_max_f32_e32 v15, 0, v15
	v_max_f32_e32 v12, 0, v12
	v_max_f32_e32 v13, 0, v13
	v_pk_mul_f32 v[16:17], v[10:11], v[10:11]
	v_lshlrev_b64 v[10:11], 13, v[154:155]
	v_pk_mul_f32 v[14:15], v[14:15], v[14:15]
	v_pk_mul_f32 v[20:21], v[12:13], v[12:13]
	v_lshl_add_u64 v[10:11], s[6:7], 0, v[10:11]
	v_pk_mul_f32 v[2:3], v[2:3], v[130:131] op_sel_hi:[1,0]
	v_lshl_add_u64 v[22:23], v[10:11], 0, v[122:123]
	v_cvt_pk_bf16_f32 v10, v14, v15
	v_cvt_pk_bf16_f32 v11, v16, v17
	v_cvt_pk_bf16_f32 v12, v18, v19
	v_cvt_pk_bf16_f32 v13, v20, v21
	v_pk_mul_f32 v[8:9], v[8:9], v[130:131] op_sel_hi:[1,0]
	v_pk_mul_f32 v[6:7], v[6:7], v[130:131] op_sel_hi:[1,0]
	v_pk_mul_f32 v[4:5], v[4:5], v[130:131] op_sel_hi:[1,0]
	v_max_f32_e32 v2, 0, v2
	v_max_f32_e32 v3, 0, v3
	global_store_dwordx4 v[22:23], v[10:13], off sc1
	v_max_f32_e32 v6, 0, v6
	v_max_f32_e32 v7, 0, v7
	v_pk_mul_f32 v[10:11], v[2:3], v[2:3]
	v_max_f32_e32 v2, 0, v8
	v_max_f32_e32 v4, 0, v4
	v_max_f32_e32 v3, 0, v9
	v_max_f32_e32 v5, 0, v5
	v_pk_mul_f32 v[6:7], v[6:7], v[6:7]
	v_pk_mul_f32 v[8:9], v[2:3], v[2:3]
	v_pk_mul_f32 v[12:13], v[4:5], v[4:5]
	v_cvt_pk_bf16_f32 v2, v6, v7
	v_cvt_pk_bf16_f32 v3, v8, v9
	v_cvt_pk_bf16_f32 v4, v10, v11
	v_cvt_pk_bf16_f32 v5, v12, v13
	global_store_dwordx4 v[22:23], v[2:5], off offset:256 sc1
	s_cbranch_vccnz .LBB0_1227
	s_andn2_b64 vcc, exec, s[4:5]
	s_cbranch_vccnz .LBB0_1226
	s_barrier
	s_branch .LBB0_1226
